# MF=4 tail-tile K-loops: software-pipelined fragments + early restage of the current LDS buffer (prefetch distance 1.5 K-steps, counted vmcnt)
# speedup vs baseline: 1.0184x; 1.0084x over previous
;     ...
;   for (int kt = 0; kt < nk; ++kt) {
;     const bool issue = kt + 1 < nk;
;     const int ibuf = buf ^ 1;
; #pragma unroll
;     for (int s2 = 0; s2 < 2; ++s2) {
;       bf16x8 bf[4], af[MF];
;       {
;         const unsigned la = lds_base + buf * 65536 + ((wm * MF) << 11) + (s2 ? lofs1 : lofs0);
;         const unsigned lb = lds_base + buf * 65536 + 32768 + ((wn * 4) << 11) + (s2 ? lofs1 : lofs0);
;         if constexpr (MF == 8) {
;           asm volatile(
;               "ds_read_b128 %0, %13\n\tds_read_b128 %1, %13 offset:2048\n\tds_read_b128 %2, %13 offset:4096\n\tds_read_b128 %3, %13 offset:6144\n\t"
;               "ds_read_b128 %4, %12\n\tds_read_b128 %5, %12 offset:2048\n\tds_read_b128 %6, %12 offset:4096\n\tds_read_b128 %7, %12 offset:6144\n\t"
;               "ds_read_b128 %8, %12 offset:8192\n\tds_read_b128 %9, %12 offset:10240\n\tds_read_b128 %10, %12 offset:12288\n\tds_read_b128 %11, %12 offset:14336\n\t"
;               "s_waitcnt lgkmcnt(0)"
;               : "=&v"(bf[0]), "=&v"(bf[1]), "=&v"(bf[2]), "=&v"(bf[3]), "=&v"(af[0]), "=&v"(af[1]), "=&v"(af[2]), "=&v"(af[3]),
;                 "=&v"(af[4]), "=&v"(af[5]), "=&v"(af[6]), "=&v"(af[7])
;               : "v"(la), "v"(lb)
;               : "memory");
;         } else {
;           asm volatile(
;               "ds_read_b128 %0, %9\n\tds_read_b128 %1, %9 offset:2048\n\tds_read_b128 %2, %9 offset:4096\n\tds_read_b128 %3, %9 offset:6144\n\t"
;               "ds_read_b128 %4, %8\n\tds_read_b128 %5, %8 offset:2048\n\tds_read_b128 %6, %8 offset:4096\n\tds_read_b128 %7, %8 offset:6144\n\t"
;               "s_waitcnt lgkmcnt(0)"
;               : "=&v"(bf[0]), "=&v"(bf[1]), "=&v"(bf[2]), "=&v"(bf[3]), "=&v"(af[0]), "=&v"(af[1]), "=&v"(af[2]), "=&v"(af[3])
;               : "v"(la), "v"(lb)
;               : "memory");
;         }
;       }
;       __builtin_amdgcn_sched_barrier(0);
;       __builtin_amdgcn_s_setprio(1);
; #pragma unroll
;       for (int m = 0; m < MF; ++m) {
; #pragma unroll
;         for (int n = 0; n < 4; ++n) acc[m][n] = mfma16(bf[n], af[m], acc[m][n]);
;         if constexpr (MF == 8) {
;           if (m & 1) {
;             __builtin_amdgcn_sched_barrier(0);
;             if (issue) {
;               if (s2 == 0) { if (m == 1) GEMM_PIECE_A(ibuf, 0); if (m == 3) GEMM_PIECE_A(ibuf, 1); if (m == 5) GEMM_PIECE_A(ibuf, 2); if (m == 7) GEMM_PIECE_A(ibuf, 3); }
.LBB0_423:
	s_barrier
	s_add_i32 s5, s5, -1
	v_lshl_add_u64 v[98:99], v[98:99], 0, s[0:1]
	v_lshl_add_u64 v[96:97], v[96:97], 0, s[0:1]
	s_cmp_eq_u32 s5, 0
	s_cbranch_scc1 .Lg4_0_exit
.LBB0_424:
	s_mov_b32 s2, s33
	s_cmp_gt_u32 s5, 2
	s_cselect_b64 s[0:1], -1, 0
	s_lshl_b32 s2, s2, 16
	v_add3_u32 v242, s2, v104, v106
	v_add3_u32 v243, s2, v105, v106
	ds_read_b128 v[80:83], v243
	ds_read_b128 v[76:79], v243 offset:2048
	ds_read_b128 v[72:75], v243 offset:4096
	ds_read_b128 v[64:67], v243 offset:6144
	ds_read_b128 v[120:123], v242
	ds_read_b128 v[88:91], v242 offset:2048
	ds_read_b128 v[84:87], v242 offset:4096
	ds_read_b128 v[68:71], v242 offset:6144
	v_add3_u32 v242, s2, v104, v107
	v_add3_u32 v243, s2, v105, v107
	s_xor_b32 s33, s33, 1
	s_lshl_b32 s34, s33, 16
	v_readfirstlane_b32 s98, v102
	v_readfirstlane_b32 s99, v111
	v_readfirstlane_b32 s100, v103
	s_add_u32 s98, s98, s2
	s_add_u32 s99, s99, s2
	s_add_u32 s100, s100, s2
	s_setprio 1
	v_mfma_f32_16x16x32_bf16 v[60:63], v[208:211], v[224:227], v[60:63]
	v_mfma_f32_16x16x32_bf16 v[56:59], v[212:215], v[224:227], v[56:59]
	v_mfma_f32_16x16x32_bf16 v[52:55], v[216:219], v[224:227], v[52:55]
	v_mfma_f32_16x16x32_bf16 v[48:51], v[220:223], v[224:227], v[48:51]
	v_mfma_f32_16x16x32_bf16 v[44:47], v[208:211], v[228:231], v[44:47]
	v_mfma_f32_16x16x32_bf16 v[40:43], v[212:215], v[228:231], v[40:43]
	v_mfma_f32_16x16x32_bf16 v[36:39], v[216:219], v[228:231], v[36:39]
	v_mfma_f32_16x16x32_bf16 v[32:35], v[220:223], v[228:231], v[32:35]
	v_mfma_f32_16x16x32_bf16 v[28:31], v[208:211], v[232:235], v[28:31]
	v_mfma_f32_16x16x32_bf16 v[24:27], v[212:215], v[232:235], v[24:27]
	v_mfma_f32_16x16x32_bf16 v[20:23], v[216:219], v[232:235], v[20:23]
	v_mfma_f32_16x16x32_bf16 v[12:15], v[220:223], v[232:235], v[12:15]
	v_mfma_f32_16x16x32_bf16 v[16:19], v[208:211], v[238:241], v[16:19]
	v_mfma_f32_16x16x32_bf16 v[8:11], v[212:215], v[238:241], v[8:11]
	v_mfma_f32_16x16x32_bf16 v[4:7], v[216:219], v[238:241], v[4:7]
	v_mfma_f32_16x16x32_bf16 v[0:3], v[220:223], v[238:241], v[0:3]
	s_setprio 0
.Lg4_0_mid:
	s_waitcnt lgkmcnt(0)
	ds_read_b128 v[208:211], v243
	ds_read_b128 v[212:215], v243 offset:2048
	ds_read_b128 v[216:219], v243 offset:4096
	ds_read_b128 v[220:223], v243 offset:6144
	ds_read_b128 v[224:227], v242
	ds_read_b128 v[228:231], v242 offset:2048
	ds_read_b128 v[232:235], v242 offset:4096
	ds_read_b128 v[238:241], v242 offset:6144
	s_setprio 1
	v_mfma_f32_16x16x32_bf16 v[60:63], v[80:83], v[120:123], v[60:63]
	v_mfma_f32_16x16x32_bf16 v[56:59], v[76:79], v[120:123], v[56:59]
	v_mfma_f32_16x16x32_bf16 v[52:55], v[72:75], v[120:123], v[52:55]
	v_mfma_f32_16x16x32_bf16 v[48:51], v[64:67], v[120:123], v[48:51]
	v_mfma_f32_16x16x32_bf16 v[44:47], v[80:83], v[88:91], v[44:47]
	v_mfma_f32_16x16x32_bf16 v[40:43], v[76:79], v[88:91], v[40:43]
	v_mfma_f32_16x16x32_bf16 v[36:39], v[72:75], v[88:91], v[36:39]
	v_mfma_f32_16x16x32_bf16 v[32:35], v[64:67], v[88:91], v[32:35]
	s_setprio 0
	s_waitcnt lgkmcnt(0)
	s_barrier
	s_cmp_eq_u64 s[0:1], 0
	s_cbranch_scc1 .Lg4_0_nodma
	s_setprio 1
	v_mfma_f32_16x16x32_bf16 v[28:31], v[80:83], v[84:87], v[28:31]
	s_mov_b32 m0, s98
	s_nop 0
	global_load_lds_dwordx4 v[96:97], off
	v_mfma_f32_16x16x32_bf16 v[24:27], v[76:79], v[84:87], v[24:27]
	s_add_u32 m0, s98, 0x400
	v_lshl_add_u64 v[254:255], v[96:97], 0, s[8:9]
	global_load_lds_dwordx4 v[254:255], off
	v_mfma_f32_16x16x32_bf16 v[20:23], v[72:75], v[84:87], v[20:23]
	s_add_u32 m0, s99, 0x8000
	s_nop 0
	global_load_lds_dwordx4 v[98:99], off
	v_mfma_f32_16x16x32_bf16 v[12:15], v[64:67], v[84:87], v[12:15]
	s_add_u32 m0, s100, 0x8400
	v_lshl_add_u64 v[254:255], v[98:99], 0, s[8:9]
	global_load_lds_dwordx4 v[254:255], off
	v_mfma_f32_16x16x32_bf16 v[16:19], v[80:83], v[68:71], v[16:19]
	s_add_u32 m0, s100, 0x8800
	v_lshl_add_u64 v[254:255], v[98:99], 0, s[10:11]
	global_load_lds_dwordx4 v[254:255], off
	v_mfma_f32_16x16x32_bf16 v[8:11], v[76:79], v[68:71], v[8:11]
	s_add_u32 m0, s100, 0x8c00
	v_lshl_add_u64 v[254:255], v[98:99], 0, s[12:13]
	global_load_lds_dwordx4 v[254:255], off
	v_mfma_f32_16x16x32_bf16 v[4:7], v[72:75], v[68:71], v[4:7]
	v_mfma_f32_16x16x32_bf16 v[0:3], v[64:67], v[68:71], v[0:3]
	s_setprio 0
	s_mov_b64 s[0:1], 0x80
	s_waitcnt vmcnt(6)
	s_branch .LBB0_423
;     ...
;   if (preloaded) { ag += 64; bg += 64; }
;   else GEMM_STAGE(0);
;   GEMM_WAIT0;
;   int buf = 0;
; #pragma unroll 1
;   for (int kt = 0; kt < nk; ++kt) {
;     const bool issue = kt + 1 < nk;
;     const int ibuf = buf ^ 1;
; #pragma unroll
;     for (int s2 = 0; s2 < 2; ++s2) {
;       bf16x8 bf[4], af[MF];
;       {
;         const unsigned la = lds_base + buf * 65536 + ((wm * MF) << 11) + (s2 ? lofs1 : lofs0);
;         const unsigned lb = lds_base + buf * 65536 + 32768 + ((wn * 4) << 11) + (s2 ? lofs1 : lofs0);
;         if constexpr (MF == 8) {
;           asm volatile(
;               "ds_read_b128 %0, %13\n\tds_read_b128 %1, %13 offset:2048\n\tds_read_b128 %2, %13 offset:4096\n\tds_read_b128 %3, %13 offset:6144\n\t"
;               "ds_read_b128 %4, %12\n\tds_read_b128 %5, %12 offset:2048\n\tds_read_b128 %6, %12 offset:4096\n\tds_read_b128 %7, %12 offset:6144\n\t"
;               "ds_read_b128 %8, %12 offset:8192\n\tds_read_b128 %9, %12 offset:10240\n\tds_read_b128 %10, %12 offset:12288\n\tds_read_b128 %11, %12 offset:14336\n\t"
;               "s_waitcnt lgkmcnt(0)"
;               : "=&v"(bf[0]), "=&v"(bf[1]), "=&v"(bf[2]), "=&v"(bf[3]), "=&v"(af[0]), "=&v"(af[1]), "=&v"(af[2]), "=&v"(af[3]),
;                 "=&v"(af[4]), "=&v"(af[5]), "=&v"(af[6]), "=&v"(af[7])
;               : "v"(la), "v"(lb)
;               : "memory");
;         } else {
;           asm volatile(
;               "ds_read_b128 %0, %9\n\tds_read_b128 %1, %9 offset:2048\n\tds_read_b128 %2, %9 offset:4096\n\tds_read_b128 %3, %9 offset:6144\n\t"
;               "ds_read_b128 %4, %8\n\tds_read_b128 %5, %8 offset:2048\n\tds_read_b128 %6, %8 offset:4096\n\tds_read_b128 %7, %8 offset:6144\n\t"
;               "s_waitcnt lgkmcnt(0)"
;               : "=&v"(bf[0]), "=&v"(bf[1]), "=&v"(bf[2]), "=&v"(bf[3]), "=&v"(af[0]), "=&v"(af[1]), "=&v"(af[2]), "=&v"(af[3])
;               : "v"(la), "v"(lb)
;               : "memory");
;         }
;       }
;       __builtin_amdgcn_sched_barrier(0);
;       __builtin_amdgcn_s_setprio(1);
; #pragma unroll
;       for (int m = 0; m < MF; ++m) {
; #pragma unroll
;         for (int n = 0; n < 4; ++n) acc[m][n] = mfma16(bf[n], af[m], acc[m][n]);
;         if constexpr (MF == 8) {
;           if (m & 1) {
;             __builtin_amdgcn_sched_barrier(0);
;             if (issue) {
.Lg4_0_nodma:
	s_setprio 1
	v_mfma_f32_16x16x32_bf16 v[28:31], v[80:83], v[84:87], v[28:31]
	v_mfma_f32_16x16x32_bf16 v[24:27], v[76:79], v[84:87], v[24:27]
	v_mfma_f32_16x16x32_bf16 v[20:23], v[72:75], v[84:87], v[20:23]
	v_mfma_f32_16x16x32_bf16 v[12:15], v[64:67], v[84:87], v[12:15]
	v_mfma_f32_16x16x32_bf16 v[16:19], v[80:83], v[68:71], v[16:19]
	v_mfma_f32_16x16x32_bf16 v[8:11], v[76:79], v[68:71], v[8:11]
	v_mfma_f32_16x16x32_bf16 v[4:7], v[72:75], v[68:71], v[4:7]
	v_mfma_f32_16x16x32_bf16 v[0:3], v[64:67], v[68:71], v[0:3]
	s_setprio 0
	s_mov_b64 s[0:1], 0
	s_waitcnt vmcnt(0)
	s_branch .LBB0_423
.Lg4_0_entry:
	s_mov_b32 s2, s33
	s_cmp_gt_u32 s5, 2
	s_cselect_b64 s[0:1], -1, 0
	s_lshl_b32 s2, s2, 16
	v_add3_u32 v242, s2, v104, v106
	v_add3_u32 v243, s2, v105, v106
	ds_read_b128 v[80:83], v243
	ds_read_b128 v[76:79], v243 offset:2048
	ds_read_b128 v[72:75], v243 offset:4096
	ds_read_b128 v[64:67], v243 offset:6144
	ds_read_b128 v[120:123], v242
	ds_read_b128 v[88:91], v242 offset:2048
	ds_read_b128 v[84:87], v242 offset:4096
	ds_read_b128 v[68:71], v242 offset:6144
	v_add3_u32 v242, s2, v104, v107
	v_add3_u32 v243, s2, v105, v107
	s_xor_b32 s33, s33, 1
	s_lshl_b32 s34, s33, 16
	v_readfirstlane_b32 s98, v102
	v_readfirstlane_b32 s99, v111
	v_readfirstlane_b32 s100, v103
	s_add_u32 s98, s98, s2
	s_add_u32 s99, s99, s2
	s_add_u32 s100, s100, s2
	s_sub_u32 vcc_lo, s34, s2
	s_add_u32 s98, s98, vcc_lo
	s_add_u32 s99, s99, vcc_lo
	s_add_u32 s100, s100, vcc_lo
	s_mov_b32 m0, s98
	s_nop 0
	global_load_lds_dwordx4 v[96:97], off
	s_add_u32 m0, s98, 0x400
	v_lshl_add_u64 v[254:255], v[96:97], 0, s[8:9]
	global_load_lds_dwordx4 v[254:255], off
	s_add_u32 m0, s99, 0x8000
	s_nop 0
	global_load_lds_dwordx4 v[98:99], off
	s_add_u32 m0, s100, 0x8400
	v_lshl_add_u64 v[254:255], v[98:99], 0, s[8:9]
	global_load_lds_dwordx4 v[254:255], off
	s_add_u32 m0, s100, 0x8800
	v_lshl_add_u64 v[254:255], v[98:99], 0, s[10:11]
	global_load_lds_dwordx4 v[254:255], off
	s_add_u32 m0, s100, 0x8c00
	v_lshl_add_u64 v[254:255], v[98:99], 0, s[12:13]
	global_load_lds_dwordx4 v[254:255], off
	s_sub_u32 s98, s98, vcc_lo
	s_sub_u32 s99, s99, vcc_lo
	s_sub_u32 s100, s100, vcc_lo
	s_mov_b64 s[0:1], 0x80
	v_lshl_add_u64 v[96:97], v[96:97], 0, s[0:1]
	v_lshl_add_u64 v[98:99], v[98:99], 0, s[0:1]
	s_branch .Lg4_0_mid
.Lg4_0_exit:
	s_setprio 1
	v_mfma_f32_16x16x32_bf16 v[60:63], v[208:211], v[224:227], v[60:63]
	v_mfma_f32_16x16x32_bf16 v[56:59], v[212:215], v[224:227], v[56:59]
	v_mfma_f32_16x16x32_bf16 v[52:55], v[216:219], v[224:227], v[52:55]
	v_mfma_f32_16x16x32_bf16 v[48:51], v[220:223], v[224:227], v[48:51]
	v_mfma_f32_16x16x32_bf16 v[44:47], v[208:211], v[228:231], v[44:47]
	v_mfma_f32_16x16x32_bf16 v[40:43], v[212:215], v[228:231], v[40:43]
	v_mfma_f32_16x16x32_bf16 v[36:39], v[216:219], v[228:231], v[36:39]
	v_mfma_f32_16x16x32_bf16 v[32:35], v[220:223], v[228:231], v[32:35]
	v_mfma_f32_16x16x32_bf16 v[28:31], v[208:211], v[232:235], v[28:31]
	v_mfma_f32_16x16x32_bf16 v[24:27], v[212:215], v[232:235], v[24:27]
	v_mfma_f32_16x16x32_bf16 v[20:23], v[216:219], v[232:235], v[20:23]
	v_mfma_f32_16x16x32_bf16 v[12:15], v[220:223], v[232:235], v[12:15]
	v_mfma_f32_16x16x32_bf16 v[16:19], v[208:211], v[238:241], v[16:19]
	v_mfma_f32_16x16x32_bf16 v[8:11], v[212:215], v[238:241], v[8:11]
	v_mfma_f32_16x16x32_bf16 v[4:7], v[216:219], v[238:241], v[4:7]
	v_mfma_f32_16x16x32_bf16 v[0:3], v[220:223], v[238:241], v[0:3]
	s_setprio 0
	s_nop 7
	s_nop 3
	s_branch .LBB0_436

;     ...
;   for (int kt = 0; kt < nk; ++kt) {
;     const bool issue = kt + 1 < nk;
;     const int ibuf = buf ^ 1;
; #pragma unroll
;     for (int s2 = 0; s2 < 2; ++s2) {
;       bf16x8 bf[4], af[MF];
;       {
;         const unsigned la = lds_base + buf * 65536 + ((wm * MF) << 11) + (s2 ? lofs1 : lofs0);
;         const unsigned lb = lds_base + buf * 65536 + 32768 + ((wn * 4) << 11) + (s2 ? lofs1 : lofs0);
;         if constexpr (MF == 8) {
;           asm volatile(
;               "ds_read_b128 %0, %13\n\tds_read_b128 %1, %13 offset:2048\n\tds_read_b128 %2, %13 offset:4096\n\tds_read_b128 %3, %13 offset:6144\n\t"
;               "ds_read_b128 %4, %12\n\tds_read_b128 %5, %12 offset:2048\n\tds_read_b128 %6, %12 offset:4096\n\tds_read_b128 %7, %12 offset:6144\n\t"
;               "ds_read_b128 %8, %12 offset:8192\n\tds_read_b128 %9, %12 offset:10240\n\tds_read_b128 %10, %12 offset:12288\n\tds_read_b128 %11, %12 offset:14336\n\t"
;               "s_waitcnt lgkmcnt(0)"
;               : "=&v"(bf[0]), "=&v"(bf[1]), "=&v"(bf[2]), "=&v"(bf[3]), "=&v"(af[0]), "=&v"(af[1]), "=&v"(af[2]), "=&v"(af[3]),
;                 "=&v"(af[4]), "=&v"(af[5]), "=&v"(af[6]), "=&v"(af[7])
;               : "v"(la), "v"(lb)
;               : "memory");
;         } else {
;           asm volatile(
;               "ds_read_b128 %0, %9\n\tds_read_b128 %1, %9 offset:2048\n\tds_read_b128 %2, %9 offset:4096\n\tds_read_b128 %3, %9 offset:6144\n\t"
;               "ds_read_b128 %4, %8\n\tds_read_b128 %5, %8 offset:2048\n\tds_read_b128 %6, %8 offset:4096\n\tds_read_b128 %7, %8 offset:6144\n\t"
;               "s_waitcnt lgkmcnt(0)"
;               : "=&v"(bf[0]), "=&v"(bf[1]), "=&v"(bf[2]), "=&v"(bf[3]), "=&v"(af[0]), "=&v"(af[1]), "=&v"(af[2]), "=&v"(af[3])
;               : "v"(la), "v"(lb)
;               : "memory");
;         }
;       }
;       __builtin_amdgcn_sched_barrier(0);
;       __builtin_amdgcn_s_setprio(1);
; #pragma unroll
;       for (int m = 0; m < MF; ++m) {
; #pragma unroll
;         for (int n = 0; n < 4; ++n) acc[m][n] = mfma16(bf[n], af[m], acc[m][n]);
;         if constexpr (MF == 8) {
;           if (m & 1) {
;             __builtin_amdgcn_sched_barrier(0);
;             if (issue) {
;               if (s2 == 0) { if (m == 1) GEMM_PIECE_A(ibuf, 0); if (m == 3) GEMM_PIECE_A(ibuf, 1); if (m == 5) GEMM_PIECE_A(ibuf, 2); if (m == 7) GEMM_PIECE_A(ibuf, 3); }
.LBB0_457:
	s_mov_b32 s2, s27
	s_cmp_gt_u32 s5, 2
	s_cselect_b64 s[0:1], -1, 0
	s_lshl_b32 s2, s2, 16
	v_add3_u32 v242, s2, v104, v106
	v_add3_u32 v243, s2, v105, v106
	ds_read_b128 v[80:83], v243
	ds_read_b128 v[76:79], v243 offset:2048
	ds_read_b128 v[72:75], v243 offset:4096
	ds_read_b128 v[64:67], v243 offset:6144
	ds_read_b128 v[120:123], v242
	ds_read_b128 v[88:91], v242 offset:2048
	ds_read_b128 v[84:87], v242 offset:4096
	ds_read_b128 v[68:71], v242 offset:6144
	v_add3_u32 v242, s2, v104, v107
	v_add3_u32 v243, s2, v105, v107
	s_xor_b32 s27, s27, 1
	s_lshl_b32 s28, s27, 16
	v_readfirstlane_b32 s98, v102
	v_readfirstlane_b32 s99, v111
	v_readfirstlane_b32 s100, v103
	s_add_u32 s98, s98, s2
	s_add_u32 s99, s99, s2
	s_add_u32 s100, s100, s2
	s_setprio 1
	v_mfma_f32_16x16x32_bf16 v[60:63], v[208:211], v[224:227], v[60:63]
	v_mfma_f32_16x16x32_bf16 v[56:59], v[212:215], v[224:227], v[56:59]
	v_mfma_f32_16x16x32_bf16 v[52:55], v[216:219], v[224:227], v[52:55]
	v_mfma_f32_16x16x32_bf16 v[48:51], v[220:223], v[224:227], v[48:51]
	v_mfma_f32_16x16x32_bf16 v[44:47], v[208:211], v[228:231], v[44:47]
	v_mfma_f32_16x16x32_bf16 v[40:43], v[212:215], v[228:231], v[40:43]
	v_mfma_f32_16x16x32_bf16 v[36:39], v[216:219], v[228:231], v[36:39]
	v_mfma_f32_16x16x32_bf16 v[32:35], v[220:223], v[228:231], v[32:35]
	v_mfma_f32_16x16x32_bf16 v[28:31], v[208:211], v[232:235], v[28:31]
	v_mfma_f32_16x16x32_bf16 v[24:27], v[212:215], v[232:235], v[24:27]
	v_mfma_f32_16x16x32_bf16 v[20:23], v[216:219], v[232:235], v[20:23]
	v_mfma_f32_16x16x32_bf16 v[12:15], v[220:223], v[232:235], v[12:15]
	v_mfma_f32_16x16x32_bf16 v[16:19], v[208:211], v[238:241], v[16:19]
	v_mfma_f32_16x16x32_bf16 v[8:11], v[212:215], v[238:241], v[8:11]
	v_mfma_f32_16x16x32_bf16 v[4:7], v[216:219], v[238:241], v[4:7]
	v_mfma_f32_16x16x32_bf16 v[0:3], v[220:223], v[238:241], v[0:3]
	s_setprio 0
.Lg4_1_mid:
	s_waitcnt lgkmcnt(0)
	ds_read_b128 v[208:211], v243
	ds_read_b128 v[212:215], v243 offset:2048
	ds_read_b128 v[216:219], v243 offset:4096
	ds_read_b128 v[220:223], v243 offset:6144
	ds_read_b128 v[224:227], v242
	ds_read_b128 v[228:231], v242 offset:2048
	ds_read_b128 v[232:235], v242 offset:4096
	ds_read_b128 v[238:241], v242 offset:6144
	s_setprio 1
	v_mfma_f32_16x16x32_bf16 v[60:63], v[80:83], v[120:123], v[60:63]
	v_mfma_f32_16x16x32_bf16 v[56:59], v[76:79], v[120:123], v[56:59]
	v_mfma_f32_16x16x32_bf16 v[52:55], v[72:75], v[120:123], v[52:55]
	v_mfma_f32_16x16x32_bf16 v[48:51], v[64:67], v[120:123], v[48:51]
	v_mfma_f32_16x16x32_bf16 v[44:47], v[80:83], v[88:91], v[44:47]
	v_mfma_f32_16x16x32_bf16 v[40:43], v[76:79], v[88:91], v[40:43]
	v_mfma_f32_16x16x32_bf16 v[36:39], v[72:75], v[88:91], v[36:39]
	v_mfma_f32_16x16x32_bf16 v[32:35], v[64:67], v[88:91], v[32:35]
	s_setprio 0
	s_waitcnt lgkmcnt(0)
	s_barrier
	s_cmp_eq_u64 s[0:1], 0
	s_cbranch_scc1 .Lg4_1_nodma
	s_setprio 1
	v_mfma_f32_16x16x32_bf16 v[28:31], v[80:83], v[84:87], v[28:31]
	s_mov_b32 m0, s98
	s_nop 0
	global_load_lds_dwordx4 v[96:97], off
	v_mfma_f32_16x16x32_bf16 v[24:27], v[76:79], v[84:87], v[24:27]
	s_add_u32 m0, s98, 0x400
	v_lshl_add_u64 v[254:255], v[96:97], 0, s[6:7]
	global_load_lds_dwordx4 v[254:255], off
	v_mfma_f32_16x16x32_bf16 v[20:23], v[72:75], v[84:87], v[20:23]
	s_add_u32 m0, s99, 0x8000
	s_nop 0
	global_load_lds_dwordx4 v[98:99], off
	v_mfma_f32_16x16x32_bf16 v[12:15], v[64:67], v[84:87], v[12:15]
	s_add_u32 m0, s100, 0x8400
	v_lshl_add_u64 v[254:255], v[98:99], 0, s[6:7]
	global_load_lds_dwordx4 v[254:255], off
	v_mfma_f32_16x16x32_bf16 v[16:19], v[80:83], v[68:71], v[16:19]
	s_add_u32 m0, s100, 0x8800
	v_lshl_add_u64 v[254:255], v[98:99], 0, s[8:9]
	global_load_lds_dwordx4 v[254:255], off
	v_mfma_f32_16x16x32_bf16 v[8:11], v[76:79], v[68:71], v[8:11]
	s_add_u32 m0, s100, 0x8c00
	v_lshl_add_u64 v[254:255], v[98:99], 0, s[10:11]
	global_load_lds_dwordx4 v[254:255], off
	v_mfma_f32_16x16x32_bf16 v[4:7], v[72:75], v[68:71], v[4:7]
	v_mfma_f32_16x16x32_bf16 v[0:3], v[64:67], v[68:71], v[0:3]
	s_setprio 0
	s_mov_b64 s[0:1], 0x80
	s_waitcnt vmcnt(6)
	s_branch .LBB0_456

; #define GEMM_STAGE(BUF)                                                    \
;   do {                                                                     \
;     _Pragma("unroll") for (int i = 0; i < APW; ++i) GEMM_PIECE_A(BUF, i);  \
;     _Pragma("unroll") for (int i = 0; i < 4; ++i) GEMM_PIECE_B(BUF, i);    \
;     ag += 64; bg += 64;                                                    \
;   } while (0)
;     ...
;   if (preloaded) { ag += 64; bg += 64; }
;   else GEMM_STAGE(0);
;   GEMM_WAIT0;
;   int buf = 0;
; #pragma unroll 1
;   for (int kt = 0; kt < nk; ++kt) {
;     const bool issue = kt + 1 < nk;
;     const int ibuf = buf ^ 1;
; #pragma unroll
;     for (int s2 = 0; s2 < 2; ++s2) {
;       bf16x8 bf[4], af[MF];
;       {
;         const unsigned la = lds_base + buf * 65536 + ((wm * MF) << 11) + (s2 ? lofs1 : lofs0);
;         const unsigned lb = lds_base + buf * 65536 + 32768 + ((wn * 4) << 11) + (s2 ? lofs1 : lofs0);
;         if constexpr (MF == 8) {
;           asm volatile(
;               "ds_read_b128 %0, %13\n\tds_read_b128 %1, %13 offset:2048\n\tds_read_b128 %2, %13 offset:4096\n\tds_read_b128 %3, %13 offset:6144\n\t"
;               "ds_read_b128 %4, %12\n\tds_read_b128 %5, %12 offset:2048\n\tds_read_b128 %6, %12 offset:4096\n\tds_read_b128 %7, %12 offset:6144\n\t"
;               "ds_read_b128 %8, %12 offset:8192\n\tds_read_b128 %9, %12 offset:10240\n\tds_read_b128 %10, %12 offset:12288\n\tds_read_b128 %11, %12 offset:14336\n\t"
;               "s_waitcnt lgkmcnt(0)"
;               : "=&v"(bf[0]), "=&v"(bf[1]), "=&v"(bf[2]), "=&v"(bf[3]), "=&v"(af[0]), "=&v"(af[1]), "=&v"(af[2]), "=&v"(af[3]),
;                 "=&v"(af[4]), "=&v"(af[5]), "=&v"(af[6]), "=&v"(af[7])
;               : "v"(la), "v"(lb)
;               : "memory");
;         } else {
;           asm volatile(
;               "ds_read_b128 %0, %9\n\tds_read_b128 %1, %9 offset:2048\n\tds_read_b128 %2, %9 offset:4096\n\tds_read_b128 %3, %9 offset:6144\n\t"
;               "ds_read_b128 %4, %8\n\tds_read_b128 %5, %8 offset:2048\n\tds_read_b128 %6, %8 offset:4096\n\tds_read_b128 %7, %8 offset:6144\n\t"
;               "s_waitcnt lgkmcnt(0)"
;               : "=&v"(bf[0]), "=&v"(bf[1]), "=&v"(bf[2]), "=&v"(bf[3]), "=&v"(af[0]), "=&v"(af[1]), "=&v"(af[2]), "=&v"(af[3])
;               : "v"(la), "v"(lb)
;               : "memory");
;         }
;       }
.Lg4_1_entry:
	s_mov_b32 s2, s27
	s_cmp_gt_u32 s5, 2
	s_cselect_b64 s[0:1], -1, 0
	s_lshl_b32 s2, s2, 16
	v_add3_u32 v242, s2, v104, v106
	v_add3_u32 v243, s2, v105, v106
	ds_read_b128 v[80:83], v243
	ds_read_b128 v[76:79], v243 offset:2048
	ds_read_b128 v[72:75], v243 offset:4096
	ds_read_b128 v[64:67], v243 offset:6144
	ds_read_b128 v[120:123], v242
	ds_read_b128 v[88:91], v242 offset:2048
	ds_read_b128 v[84:87], v242 offset:4096
	ds_read_b128 v[68:71], v242 offset:6144
	v_add3_u32 v242, s2, v104, v107
	v_add3_u32 v243, s2, v105, v107
	s_xor_b32 s27, s27, 1
	s_lshl_b32 s28, s27, 16
	v_readfirstlane_b32 s98, v102
	v_readfirstlane_b32 s99, v111
	v_readfirstlane_b32 s100, v103
	s_add_u32 s98, s98, s2
	s_add_u32 s99, s99, s2
	s_add_u32 s100, s100, s2
	s_sub_u32 vcc_lo, s28, s2
	s_add_u32 s98, s98, vcc_lo
	s_add_u32 s99, s99, vcc_lo
	s_add_u32 s100, s100, vcc_lo
	s_mov_b32 m0, s98
	s_nop 0
	global_load_lds_dwordx4 v[96:97], off
	s_add_u32 m0, s98, 0x400
	v_lshl_add_u64 v[254:255], v[96:97], 0, s[6:7]
	global_load_lds_dwordx4 v[254:255], off
	s_add_u32 m0, s99, 0x8000
	s_nop 0
	global_load_lds_dwordx4 v[98:99], off
	s_add_u32 m0, s100, 0x8400
	v_lshl_add_u64 v[254:255], v[98:99], 0, s[6:7]
	global_load_lds_dwordx4 v[254:255], off
	s_add_u32 m0, s100, 0x8800
	v_lshl_add_u64 v[254:255], v[98:99], 0, s[8:9]
	global_load_lds_dwordx4 v[254:255], off
	s_add_u32 m0, s100, 0x8c00
	v_lshl_add_u64 v[254:255], v[98:99], 0, s[10:11]
	global_load_lds_dwordx4 v[254:255], off
	s_sub_u32 s98, s98, vcc_lo
	s_sub_u32 s99, s99, vcc_lo
	s_sub_u32 s100, s100, vcc_lo
	s_mov_b64 s[0:1], 0x80
	v_lshl_add_u64 v[96:97], v[96:97], 0, s[0:1]
	v_lshl_add_u64 v[98:99], v[98:99], 0, s[0:1]
	s_branch .Lg4_1_mid

;     ...
;   for (int kt = 0; kt < nk; ++kt) {
;     const bool issue = kt + 1 < nk;
;     const int ibuf = buf ^ 1;
; #pragma unroll
;     for (int s2 = 0; s2 < 2; ++s2) {
;       bf16x8 bf[4], af[MF];
;       {
;         const unsigned la = lds_base + buf * 65536 + ((wm * MF) << 11) + (s2 ? lofs1 : lofs0);
;         const unsigned lb = lds_base + buf * 65536 + 32768 + ((wn * 4) << 11) + (s2 ? lofs1 : lofs0);
;         if constexpr (MF == 8) {
;           asm volatile(
;               "ds_read_b128 %0, %13\n\tds_read_b128 %1, %13 offset:2048\n\tds_read_b128 %2, %13 offset:4096\n\tds_read_b128 %3, %13 offset:6144\n\t"
;               "ds_read_b128 %4, %12\n\tds_read_b128 %5, %12 offset:2048\n\tds_read_b128 %6, %12 offset:4096\n\tds_read_b128 %7, %12 offset:6144\n\t"
;               "ds_read_b128 %8, %12 offset:8192\n\tds_read_b128 %9, %12 offset:10240\n\tds_read_b128 %10, %12 offset:12288\n\tds_read_b128 %11, %12 offset:14336\n\t"
;               "s_waitcnt lgkmcnt(0)"
;               : "=&v"(bf[0]), "=&v"(bf[1]), "=&v"(bf[2]), "=&v"(bf[3]), "=&v"(af[0]), "=&v"(af[1]), "=&v"(af[2]), "=&v"(af[3]),
;                 "=&v"(af[4]), "=&v"(af[5]), "=&v"(af[6]), "=&v"(af[7])
;               : "v"(la), "v"(lb)
;               : "memory");
;         } else {
;           asm volatile(
;               "ds_read_b128 %0, %9\n\tds_read_b128 %1, %9 offset:2048\n\tds_read_b128 %2, %9 offset:4096\n\tds_read_b128 %3, %9 offset:6144\n\t"
;               "ds_read_b128 %4, %8\n\tds_read_b128 %5, %8 offset:2048\n\tds_read_b128 %6, %8 offset:4096\n\tds_read_b128 %7, %8 offset:6144\n\t"
;               "s_waitcnt lgkmcnt(0)"
;               : "=&v"(bf[0]), "=&v"(bf[1]), "=&v"(bf[2]), "=&v"(bf[3]), "=&v"(af[0]), "=&v"(af[1]), "=&v"(af[2]), "=&v"(af[3])
;               : "v"(la), "v"(lb)
;               : "memory");
;         }
;       }
;       __builtin_amdgcn_sched_barrier(0);
;       __builtin_amdgcn_s_setprio(1);
; #pragma unroll
;       for (int m = 0; m < MF; ++m) {
; #pragma unroll
;         for (int n = 0; n < 4; ++n) acc[m][n] = mfma16(bf[n], af[m], acc[m][n]);
;         if constexpr (MF == 8) {
;           if (m & 1) {
;             __builtin_amdgcn_sched_barrier(0);
;             if (issue) {
;               if (s2 == 0) { if (m == 1) GEMM_PIECE_A(ibuf, 0); if (m == 3) GEMM_PIECE_A(ibuf, 1); if (m == 5) GEMM_PIECE_A(ibuf, 2); if (m == 7) GEMM_PIECE_A(ibuf, 3); }
.LBB0_627:
	s_add_i32 s34, s34, 1
	s_barrier
	v_lshl_add_u64 v[96:97], v[96:97], 0, s[4:5]
	v_lshl_add_u64 v[98:99], v[98:99], 0, s[4:5]
	s_cmp_eq_u32 s34, 44
	s_cbranch_scc1 .Lg4_2_exit
.LBB0_628:
	s_mov_b32 s4, s35
	s_cmp_lt_u32 s34, 42
	s_cselect_b64 s[20:21], -1, 0
	s_lshl_b32 s4, s4, 16
	v_add3_u32 v242, s4, v104, v106
	v_add3_u32 v243, s4, v105, v106
	ds_read_b128 v[80:83], v243
	ds_read_b128 v[76:79], v243 offset:2048
	ds_read_b128 v[72:75], v243 offset:4096
	ds_read_b128 v[64:67], v243 offset:6144
	ds_read_b128 v[120:123], v242
	ds_read_b128 v[88:91], v242 offset:2048
	ds_read_b128 v[84:87], v242 offset:4096
	ds_read_b128 v[68:71], v242 offset:6144
	v_add3_u32 v242, s4, v104, v107
	v_add3_u32 v243, s4, v105, v107
	s_xor_b32 s35, s35, 1
	s_lshl_b32 s36, s35, 16
	v_readfirstlane_b32 s98, v102
	v_readfirstlane_b32 s99, v110
	v_readfirstlane_b32 s100, v103
	s_add_u32 s98, s98, s4
	s_add_u32 s99, s99, s4
	s_add_u32 s100, s100, s4
	s_setprio 1
	v_mfma_f32_16x16x32_bf16 v[60:63], v[208:211], v[224:227], v[60:63]
	v_mfma_f32_16x16x32_bf16 v[56:59], v[212:215], v[224:227], v[56:59]
	v_mfma_f32_16x16x32_bf16 v[52:55], v[216:219], v[224:227], v[52:55]
	v_mfma_f32_16x16x32_bf16 v[48:51], v[220:223], v[224:227], v[48:51]
	v_mfma_f32_16x16x32_bf16 v[44:47], v[208:211], v[228:231], v[44:47]
	v_mfma_f32_16x16x32_bf16 v[40:43], v[212:215], v[228:231], v[40:43]
	v_mfma_f32_16x16x32_bf16 v[28:31], v[216:219], v[228:231], v[28:31]
	v_mfma_f32_16x16x32_bf16 v[20:23], v[220:223], v[228:231], v[20:23]
	v_mfma_f32_16x16x32_bf16 v[36:39], v[208:211], v[232:235], v[36:39]
	v_mfma_f32_16x16x32_bf16 v[32:35], v[212:215], v[232:235], v[32:35]
	v_mfma_f32_16x16x32_bf16 v[24:27], v[216:219], v[232:235], v[24:27]
	v_mfma_f32_16x16x32_bf16 v[16:19], v[220:223], v[232:235], v[16:19]
	v_mfma_f32_16x16x32_bf16 v[12:15], v[208:211], v[238:241], v[12:15]
	v_mfma_f32_16x16x32_bf16 v[8:11], v[212:215], v[238:241], v[8:11]
	v_mfma_f32_16x16x32_bf16 v[4:7], v[216:219], v[238:241], v[4:7]
	v_mfma_f32_16x16x32_bf16 v[0:3], v[220:223], v[238:241], v[0:3]
	s_setprio 0
.Lg4_2_mid:
	s_waitcnt lgkmcnt(0)
	ds_read_b128 v[208:211], v243
	ds_read_b128 v[212:215], v243 offset:2048
	ds_read_b128 v[216:219], v243 offset:4096
	ds_read_b128 v[220:223], v243 offset:6144
	ds_read_b128 v[224:227], v242
	ds_read_b128 v[228:231], v242 offset:2048
	ds_read_b128 v[232:235], v242 offset:4096
	ds_read_b128 v[238:241], v242 offset:6144
	s_setprio 1
	v_mfma_f32_16x16x32_bf16 v[60:63], v[80:83], v[120:123], v[60:63]
	v_mfma_f32_16x16x32_bf16 v[56:59], v[76:79], v[120:123], v[56:59]
	v_mfma_f32_16x16x32_bf16 v[52:55], v[72:75], v[120:123], v[52:55]
	v_mfma_f32_16x16x32_bf16 v[48:51], v[64:67], v[120:123], v[48:51]
	v_mfma_f32_16x16x32_bf16 v[44:47], v[80:83], v[88:91], v[44:47]
	v_mfma_f32_16x16x32_bf16 v[40:43], v[76:79], v[88:91], v[40:43]
	v_mfma_f32_16x16x32_bf16 v[28:31], v[72:75], v[88:91], v[28:31]
	v_mfma_f32_16x16x32_bf16 v[20:23], v[64:67], v[88:91], v[20:23]
	s_setprio 0
	s_waitcnt lgkmcnt(0)
	s_barrier
	s_cmp_eq_u64 s[20:21], 0
	s_cbranch_scc1 .Lg4_2_nodma
	s_setprio 1
	v_mfma_f32_16x16x32_bf16 v[36:39], v[80:83], v[84:87], v[36:39]
	s_mov_b32 m0, s98
	s_nop 0
	global_load_lds_dwordx4 v[98:99], off
	v_mfma_f32_16x16x32_bf16 v[32:35], v[76:79], v[84:87], v[32:35]
	s_add_u32 m0, s98, 0x400
	v_lshl_add_u64 v[254:255], v[98:99], 0, s[12:13]
	global_load_lds_dwordx4 v[254:255], off
	v_mfma_f32_16x16x32_bf16 v[24:27], v[72:75], v[84:87], v[24:27]
	s_add_u32 m0, s99, 0x8000
	s_nop 0
	global_load_lds_dwordx4 v[96:97], off
	v_mfma_f32_16x16x32_bf16 v[16:19], v[64:67], v[84:87], v[16:19]
	s_add_u32 m0, s100, 0x8400
	v_lshl_add_u64 v[254:255], v[96:97], 0, s[12:13]
	global_load_lds_dwordx4 v[254:255], off
	v_mfma_f32_16x16x32_bf16 v[12:15], v[80:83], v[68:71], v[12:15]
	s_add_u32 m0, s100, 0x8800
	v_lshl_add_u64 v[254:255], v[96:97], 0, s[14:15]
	global_load_lds_dwordx4 v[254:255], off
	v_mfma_f32_16x16x32_bf16 v[8:11], v[76:79], v[68:71], v[8:11]
	s_add_u32 m0, s100, 0x8c00
	v_lshl_add_u64 v[254:255], v[96:97], 0, s[16:17]
	global_load_lds_dwordx4 v[254:255], off
	v_mfma_f32_16x16x32_bf16 v[4:7], v[72:75], v[68:71], v[4:7]
	v_mfma_f32_16x16x32_bf16 v[0:3], v[64:67], v[68:71], v[0:3]
	s_setprio 0
	s_mov_b64 s[4:5], 0x80
	s_waitcnt vmcnt(6)
	s_branch .LBB0_627
;     ...
;   if (preloaded) { ag += 64; bg += 64; }
;   else GEMM_STAGE(0);
;   GEMM_WAIT0;
;   int buf = 0;
; #pragma unroll 1
;   for (int kt = 0; kt < nk; ++kt) {
;     const bool issue = kt + 1 < nk;
;     const int ibuf = buf ^ 1;
; #pragma unroll
;     for (int s2 = 0; s2 < 2; ++s2) {
;       bf16x8 bf[4], af[MF];
;       {
;         const unsigned la = lds_base + buf * 65536 + ((wm * MF) << 11) + (s2 ? lofs1 : lofs0);
;         const unsigned lb = lds_base + buf * 65536 + 32768 + ((wn * 4) << 11) + (s2 ? lofs1 : lofs0);
;         if constexpr (MF == 8) {
;           asm volatile(
;               "ds_read_b128 %0, %13\n\tds_read_b128 %1, %13 offset:2048\n\tds_read_b128 %2, %13 offset:4096\n\tds_read_b128 %3, %13 offset:6144\n\t"
;               "ds_read_b128 %4, %12\n\tds_read_b128 %5, %12 offset:2048\n\tds_read_b128 %6, %12 offset:4096\n\tds_read_b128 %7, %12 offset:6144\n\t"
;               "ds_read_b128 %8, %12 offset:8192\n\tds_read_b128 %9, %12 offset:10240\n\tds_read_b128 %10, %12 offset:12288\n\tds_read_b128 %11, %12 offset:14336\n\t"
;               "s_waitcnt lgkmcnt(0)"
;               : "=&v"(bf[0]), "=&v"(bf[1]), "=&v"(bf[2]), "=&v"(bf[3]), "=&v"(af[0]), "=&v"(af[1]), "=&v"(af[2]), "=&v"(af[3]),
;                 "=&v"(af[4]), "=&v"(af[5]), "=&v"(af[6]), "=&v"(af[7])
;               : "v"(la), "v"(lb)
;               : "memory");
;         } else {
;           asm volatile(
;               "ds_read_b128 %0, %9\n\tds_read_b128 %1, %9 offset:2048\n\tds_read_b128 %2, %9 offset:4096\n\tds_read_b128 %3, %9 offset:6144\n\t"
;               "ds_read_b128 %4, %8\n\tds_read_b128 %5, %8 offset:2048\n\tds_read_b128 %6, %8 offset:4096\n\tds_read_b128 %7, %8 offset:6144\n\t"
;               "s_waitcnt lgkmcnt(0)"
;               : "=&v"(bf[0]), "=&v"(bf[1]), "=&v"(bf[2]), "=&v"(bf[3]), "=&v"(af[0]), "=&v"(af[1]), "=&v"(af[2]), "=&v"(af[3])
;               : "v"(la), "v"(lb)
;               : "memory");
;         }
;       }
;       __builtin_amdgcn_sched_barrier(0);
;       __builtin_amdgcn_s_setprio(1);
; #pragma unroll
;       for (int m = 0; m < MF; ++m) {
; #pragma unroll
;         for (int n = 0; n < 4; ++n) acc[m][n] = mfma16(bf[n], af[m], acc[m][n]);
;         if constexpr (MF == 8) {
;           if (m & 1) {
;             __builtin_amdgcn_sched_barrier(0);
;             if (issue) {
.Lg4_2_nodma:
	s_setprio 1
	v_mfma_f32_16x16x32_bf16 v[36:39], v[80:83], v[84:87], v[36:39]
	v_mfma_f32_16x16x32_bf16 v[32:35], v[76:79], v[84:87], v[32:35]
	v_mfma_f32_16x16x32_bf16 v[24:27], v[72:75], v[84:87], v[24:27]
	v_mfma_f32_16x16x32_bf16 v[16:19], v[64:67], v[84:87], v[16:19]
	v_mfma_f32_16x16x32_bf16 v[12:15], v[80:83], v[68:71], v[12:15]
	v_mfma_f32_16x16x32_bf16 v[8:11], v[76:79], v[68:71], v[8:11]
	v_mfma_f32_16x16x32_bf16 v[4:7], v[72:75], v[68:71], v[4:7]
	v_mfma_f32_16x16x32_bf16 v[0:3], v[64:67], v[68:71], v[0:3]
	s_setprio 0
	s_mov_b64 s[4:5], 0
	s_waitcnt vmcnt(0)
	s_branch .LBB0_627
.Lg4_2_entry:
	s_mov_b32 s4, s35
	s_cmp_lt_u32 s34, 42
	s_cselect_b64 s[20:21], -1, 0
	s_lshl_b32 s4, s4, 16
	v_add3_u32 v242, s4, v104, v106
	v_add3_u32 v243, s4, v105, v106
	ds_read_b128 v[80:83], v243
	ds_read_b128 v[76:79], v243 offset:2048
	ds_read_b128 v[72:75], v243 offset:4096
	ds_read_b128 v[64:67], v243 offset:6144
	ds_read_b128 v[120:123], v242
	ds_read_b128 v[88:91], v242 offset:2048
	ds_read_b128 v[84:87], v242 offset:4096
	ds_read_b128 v[68:71], v242 offset:6144
	v_add3_u32 v242, s4, v104, v107
	v_add3_u32 v243, s4, v105, v107
	s_xor_b32 s35, s35, 1
	s_lshl_b32 s36, s35, 16
	v_readfirstlane_b32 s98, v102
	v_readfirstlane_b32 s99, v110
	v_readfirstlane_b32 s100, v103
	s_add_u32 s98, s98, s4
	s_add_u32 s99, s99, s4
	s_add_u32 s100, s100, s4
	s_sub_u32 vcc_lo, s36, s4
	s_add_u32 s98, s98, vcc_lo
	s_add_u32 s99, s99, vcc_lo
	s_add_u32 s100, s100, vcc_lo
	s_mov_b32 m0, s98
	s_nop 0
	global_load_lds_dwordx4 v[98:99], off
	s_add_u32 m0, s98, 0x400
	v_lshl_add_u64 v[254:255], v[98:99], 0, s[12:13]
	global_load_lds_dwordx4 v[254:255], off
	s_add_u32 m0, s99, 0x8000
	s_nop 0
	global_load_lds_dwordx4 v[96:97], off
	s_add_u32 m0, s100, 0x8400
	v_lshl_add_u64 v[254:255], v[96:97], 0, s[12:13]
	global_load_lds_dwordx4 v[254:255], off
	s_add_u32 m0, s100, 0x8800
	v_lshl_add_u64 v[254:255], v[96:97], 0, s[14:15]
	global_load_lds_dwordx4 v[254:255], off
	s_add_u32 m0, s100, 0x8c00
	v_lshl_add_u64 v[254:255], v[96:97], 0, s[16:17]
	global_load_lds_dwordx4 v[254:255], off
	s_sub_u32 s98, s98, vcc_lo
	s_sub_u32 s99, s99, vcc_lo
	s_sub_u32 s100, s100, vcc_lo
	s_mov_b64 s[4:5], 0x80
	v_lshl_add_u64 v[98:99], v[98:99], 0, s[4:5]
	v_lshl_add_u64 v[96:97], v[96:97], 0, s[4:5]
	s_branch .Lg4_2_mid
.Lg4_2_exit:
	s_setprio 1
	v_mfma_f32_16x16x32_bf16 v[60:63], v[208:211], v[224:227], v[60:63]
	v_mfma_f32_16x16x32_bf16 v[56:59], v[212:215], v[224:227], v[56:59]
	v_mfma_f32_16x16x32_bf16 v[52:55], v[216:219], v[224:227], v[52:55]
	v_mfma_f32_16x16x32_bf16 v[48:51], v[220:223], v[224:227], v[48:51]
	v_mfma_f32_16x16x32_bf16 v[44:47], v[208:211], v[228:231], v[44:47]
	v_mfma_f32_16x16x32_bf16 v[40:43], v[212:215], v[228:231], v[40:43]
	v_mfma_f32_16x16x32_bf16 v[28:31], v[216:219], v[228:231], v[28:31]
	v_mfma_f32_16x16x32_bf16 v[20:23], v[220:223], v[228:231], v[20:23]
	v_mfma_f32_16x16x32_bf16 v[36:39], v[208:211], v[232:235], v[36:39]
	v_mfma_f32_16x16x32_bf16 v[32:35], v[212:215], v[232:235], v[32:35]
	v_mfma_f32_16x16x32_bf16 v[24:27], v[216:219], v[232:235], v[24:27]
	v_mfma_f32_16x16x32_bf16 v[16:19], v[220:223], v[232:235], v[16:19]
	v_mfma_f32_16x16x32_bf16 v[12:15], v[208:211], v[238:241], v[12:15]
	v_mfma_f32_16x16x32_bf16 v[8:11], v[212:215], v[238:241], v[8:11]
	v_mfma_f32_16x16x32_bf16 v[4:7], v[216:219], v[238:241], v[4:7]
	v_mfma_f32_16x16x32_bf16 v[0:3], v[220:223], v[238:241], v[0:3]
	s_setprio 0
	s_nop 7
	s_nop 3
	s_branch .LBB0_640

;     ...
;   for (int kt = 0; kt < nk; ++kt) {
;     const bool issue = kt + 1 < nk;
;     const int ibuf = buf ^ 1;
; #pragma unroll
;     for (int s2 = 0; s2 < 2; ++s2) {
;       bf16x8 bf[4], af[MF];
;       {
;         const unsigned la = lds_base + buf * 65536 + ((wm * MF) << 11) + (s2 ? lofs1 : lofs0);
;         const unsigned lb = lds_base + buf * 65536 + 32768 + ((wn * 4) << 11) + (s2 ? lofs1 : lofs0);
;         if constexpr (MF == 8) {
;           asm volatile(
;               "ds_read_b128 %0, %13\n\tds_read_b128 %1, %13 offset:2048\n\tds_read_b128 %2, %13 offset:4096\n\tds_read_b128 %3, %13 offset:6144\n\t"
;               "ds_read_b128 %4, %12\n\tds_read_b128 %5, %12 offset:2048\n\tds_read_b128 %6, %12 offset:4096\n\tds_read_b128 %7, %12 offset:6144\n\t"
;               "ds_read_b128 %8, %12 offset:8192\n\tds_read_b128 %9, %12 offset:10240\n\tds_read_b128 %10, %12 offset:12288\n\tds_read_b128 %11, %12 offset:14336\n\t"
;               "s_waitcnt lgkmcnt(0)"
;               : "=&v"(bf[0]), "=&v"(bf[1]), "=&v"(bf[2]), "=&v"(bf[3]), "=&v"(af[0]), "=&v"(af[1]), "=&v"(af[2]), "=&v"(af[3]),
;                 "=&v"(af[4]), "=&v"(af[5]), "=&v"(af[6]), "=&v"(af[7])
;               : "v"(la), "v"(lb)
;               : "memory");
;         } else {
;           asm volatile(
;               "ds_read_b128 %0, %9\n\tds_read_b128 %1, %9 offset:2048\n\tds_read_b128 %2, %9 offset:4096\n\tds_read_b128 %3, %9 offset:6144\n\t"
;               "ds_read_b128 %4, %8\n\tds_read_b128 %5, %8 offset:2048\n\tds_read_b128 %6, %8 offset:4096\n\tds_read_b128 %7, %8 offset:6144\n\t"
;               "s_waitcnt lgkmcnt(0)"
;               : "=&v"(bf[0]), "=&v"(bf[1]), "=&v"(bf[2]), "=&v"(bf[3]), "=&v"(af[0]), "=&v"(af[1]), "=&v"(af[2]), "=&v"(af[3])
;               : "v"(la), "v"(lb)
;               : "memory");
;         }
;       }
;       __builtin_amdgcn_sched_barrier(0);
;       __builtin_amdgcn_s_setprio(1);
; #pragma unroll
;       for (int m = 0; m < MF; ++m) {
; #pragma unroll
;         for (int n = 0; n < 4; ++n) acc[m][n] = mfma16(bf[n], af[m], acc[m][n]);
;         if constexpr (MF == 8) {
;           if (m & 1) {
;             __builtin_amdgcn_sched_barrier(0);
;             if (issue) {
;               if (s2 == 0) { if (m == 1) GEMM_PIECE_A(ibuf, 0); if (m == 3) GEMM_PIECE_A(ibuf, 1); if (m == 5) GEMM_PIECE_A(ibuf, 2); if (m == 7) GEMM_PIECE_A(ibuf, 3); }
.LBB0_672:
	s_add_i32 s29, s29, 1
	s_barrier
	v_lshl_add_u64 v[96:97], v[96:97], 0, s[4:5]
	v_lshl_add_u64 v[98:99], v[98:99], 0, s[4:5]
	s_cmp_eq_u32 s29, 44
	s_cbranch_scc1 .Lg4_3_exit
.LBB0_673:
	s_mov_b32 s4, s30
	s_cmp_lt_u32 s29, 42
	s_cselect_b64 s[20:21], -1, 0
	s_lshl_b32 s4, s4, 16
	v_add3_u32 v242, s4, v104, v106
	v_add3_u32 v243, s4, v105, v106
	ds_read_b128 v[80:83], v243
	ds_read_b128 v[76:79], v243 offset:2048
	ds_read_b128 v[72:75], v243 offset:4096
	ds_read_b128 v[64:67], v243 offset:6144
	ds_read_b128 v[120:123], v242
	ds_read_b128 v[88:91], v242 offset:2048
	ds_read_b128 v[84:87], v242 offset:4096
	ds_read_b128 v[68:71], v242 offset:6144
	v_add3_u32 v242, s4, v104, v107
	v_add3_u32 v243, s4, v105, v107
	s_xor_b32 s30, s30, 1
	s_lshl_b32 s31, s30, 16
	v_readfirstlane_b32 s98, v102
	v_readfirstlane_b32 s99, v110
	v_readfirstlane_b32 s100, v103
	s_add_u32 s98, s98, s4
	s_add_u32 s99, s99, s4
	s_add_u32 s100, s100, s4
	s_setprio 1
	v_mfma_f32_16x16x32_bf16 v[60:63], v[208:211], v[224:227], v[60:63]
	v_mfma_f32_16x16x32_bf16 v[56:59], v[212:215], v[224:227], v[56:59]
	v_mfma_f32_16x16x32_bf16 v[52:55], v[216:219], v[224:227], v[52:55]
	v_mfma_f32_16x16x32_bf16 v[48:51], v[220:223], v[224:227], v[48:51]
	v_mfma_f32_16x16x32_bf16 v[44:47], v[208:211], v[228:231], v[44:47]
	v_mfma_f32_16x16x32_bf16 v[40:43], v[212:215], v[228:231], v[40:43]
	v_mfma_f32_16x16x32_bf16 v[28:31], v[216:219], v[228:231], v[28:31]
	v_mfma_f32_16x16x32_bf16 v[20:23], v[220:223], v[228:231], v[20:23]
	v_mfma_f32_16x16x32_bf16 v[36:39], v[208:211], v[232:235], v[36:39]
	v_mfma_f32_16x16x32_bf16 v[32:35], v[212:215], v[232:235], v[32:35]
	v_mfma_f32_16x16x32_bf16 v[24:27], v[216:219], v[232:235], v[24:27]
	v_mfma_f32_16x16x32_bf16 v[16:19], v[220:223], v[232:235], v[16:19]
	v_mfma_f32_16x16x32_bf16 v[12:15], v[208:211], v[238:241], v[12:15]
	v_mfma_f32_16x16x32_bf16 v[8:11], v[212:215], v[238:241], v[8:11]
	v_mfma_f32_16x16x32_bf16 v[4:7], v[216:219], v[238:241], v[4:7]
	v_mfma_f32_16x16x32_bf16 v[0:3], v[220:223], v[238:241], v[0:3]
	s_setprio 0
.Lg4_3_mid:
	s_waitcnt lgkmcnt(0)
	ds_read_b128 v[208:211], v243
	ds_read_b128 v[212:215], v243 offset:2048
	ds_read_b128 v[216:219], v243 offset:4096
	ds_read_b128 v[220:223], v243 offset:6144
	ds_read_b128 v[224:227], v242
	ds_read_b128 v[228:231], v242 offset:2048
	ds_read_b128 v[232:235], v242 offset:4096
	ds_read_b128 v[238:241], v242 offset:6144
	s_setprio 1
	v_mfma_f32_16x16x32_bf16 v[60:63], v[80:83], v[120:123], v[60:63]
	v_mfma_f32_16x16x32_bf16 v[56:59], v[76:79], v[120:123], v[56:59]
	v_mfma_f32_16x16x32_bf16 v[52:55], v[72:75], v[120:123], v[52:55]
	v_mfma_f32_16x16x32_bf16 v[48:51], v[64:67], v[120:123], v[48:51]
	v_mfma_f32_16x16x32_bf16 v[44:47], v[80:83], v[88:91], v[44:47]
	v_mfma_f32_16x16x32_bf16 v[40:43], v[76:79], v[88:91], v[40:43]
	v_mfma_f32_16x16x32_bf16 v[28:31], v[72:75], v[88:91], v[28:31]
	v_mfma_f32_16x16x32_bf16 v[20:23], v[64:67], v[88:91], v[20:23]
	s_setprio 0
	s_waitcnt lgkmcnt(0)
	s_barrier
	s_cmp_eq_u64 s[20:21], 0
	s_cbranch_scc1 .Lg4_3_nodma
	s_setprio 1
	v_mfma_f32_16x16x32_bf16 v[36:39], v[80:83], v[84:87], v[36:39]
	s_mov_b32 m0, s98
	s_nop 0
	global_load_lds_dwordx4 v[98:99], off
	v_mfma_f32_16x16x32_bf16 v[32:35], v[76:79], v[84:87], v[32:35]
	s_add_u32 m0, s98, 0x400
	v_lshl_add_u64 v[254:255], v[98:99], 0, s[8:9]
	global_load_lds_dwordx4 v[254:255], off
	v_mfma_f32_16x16x32_bf16 v[24:27], v[72:75], v[84:87], v[24:27]
	s_add_u32 m0, s99, 0x8000
	s_nop 0
	global_load_lds_dwordx4 v[96:97], off
	v_mfma_f32_16x16x32_bf16 v[16:19], v[64:67], v[84:87], v[16:19]
	s_add_u32 m0, s100, 0x8400
	v_lshl_add_u64 v[254:255], v[96:97], 0, s[8:9]
	global_load_lds_dwordx4 v[254:255], off
	v_mfma_f32_16x16x32_bf16 v[12:15], v[80:83], v[68:71], v[12:15]
	s_add_u32 m0, s100, 0x8800
	v_lshl_add_u64 v[254:255], v[96:97], 0, s[10:11]
	global_load_lds_dwordx4 v[254:255], off
	v_mfma_f32_16x16x32_bf16 v[8:11], v[76:79], v[68:71], v[8:11]
	s_add_u32 m0, s100, 0x8c00
	v_lshl_add_u64 v[254:255], v[96:97], 0, s[12:13]
	global_load_lds_dwordx4 v[254:255], off
	v_mfma_f32_16x16x32_bf16 v[4:7], v[72:75], v[68:71], v[4:7]
	v_mfma_f32_16x16x32_bf16 v[0:3], v[64:67], v[68:71], v[0:3]
	s_setprio 0
	s_mov_b64 s[4:5], 0x80
	s_waitcnt vmcnt(6)
	s_branch .LBB0_672

; #define GEMM_STAGE(BUF)                                                    \
;   do {                                                                     \
;     _Pragma("unroll") for (int i = 0; i < APW; ++i) GEMM_PIECE_A(BUF, i);  \
;     _Pragma("unroll") for (int i = 0; i < 4; ++i) GEMM_PIECE_B(BUF, i);    \
;     ag += 64; bg += 64;                                                    \
;   } while (0)
;     ...
;   if (preloaded) { ag += 64; bg += 64; }
;   else GEMM_STAGE(0);
;   GEMM_WAIT0;
;   int buf = 0;
; #pragma unroll 1
;   for (int kt = 0; kt < nk; ++kt) {
;     const bool issue = kt + 1 < nk;
;     const int ibuf = buf ^ 1;
; #pragma unroll
;     for (int s2 = 0; s2 < 2; ++s2) {
;       bf16x8 bf[4], af[MF];
;       {
;         const unsigned la = lds_base + buf * 65536 + ((wm * MF) << 11) + (s2 ? lofs1 : lofs0);
;         const unsigned lb = lds_base + buf * 65536 + 32768 + ((wn * 4) << 11) + (s2 ? lofs1 : lofs0);
;         if constexpr (MF == 8) {
;           asm volatile(
;               "ds_read_b128 %0, %13\n\tds_read_b128 %1, %13 offset:2048\n\tds_read_b128 %2, %13 offset:4096\n\tds_read_b128 %3, %13 offset:6144\n\t"
;               "ds_read_b128 %4, %12\n\tds_read_b128 %5, %12 offset:2048\n\tds_read_b128 %6, %12 offset:4096\n\tds_read_b128 %7, %12 offset:6144\n\t"
;               "ds_read_b128 %8, %12 offset:8192\n\tds_read_b128 %9, %12 offset:10240\n\tds_read_b128 %10, %12 offset:12288\n\tds_read_b128 %11, %12 offset:14336\n\t"
;               "s_waitcnt lgkmcnt(0)"
;               : "=&v"(bf[0]), "=&v"(bf[1]), "=&v"(bf[2]), "=&v"(bf[3]), "=&v"(af[0]), "=&v"(af[1]), "=&v"(af[2]), "=&v"(af[3]),
;                 "=&v"(af[4]), "=&v"(af[5]), "=&v"(af[6]), "=&v"(af[7])
;               : "v"(la), "v"(lb)
;               : "memory");
;         } else {
;           asm volatile(
;               "ds_read_b128 %0, %9\n\tds_read_b128 %1, %9 offset:2048\n\tds_read_b128 %2, %9 offset:4096\n\tds_read_b128 %3, %9 offset:6144\n\t"
;               "ds_read_b128 %4, %8\n\tds_read_b128 %5, %8 offset:2048\n\tds_read_b128 %6, %8 offset:4096\n\tds_read_b128 %7, %8 offset:6144\n\t"
;               "s_waitcnt lgkmcnt(0)"
;               : "=&v"(bf[0]), "=&v"(bf[1]), "=&v"(bf[2]), "=&v"(bf[3]), "=&v"(af[0]), "=&v"(af[1]), "=&v"(af[2]), "=&v"(af[3])
;               : "v"(la), "v"(lb)
;               : "memory");
;         }
;       }
.Lg4_3_entry:
	s_mov_b32 s4, s30
	s_cmp_lt_u32 s29, 42
	s_cselect_b64 s[20:21], -1, 0
	s_lshl_b32 s4, s4, 16
	v_add3_u32 v242, s4, v104, v106
	v_add3_u32 v243, s4, v105, v106
	ds_read_b128 v[80:83], v243
	ds_read_b128 v[76:79], v243 offset:2048
	ds_read_b128 v[72:75], v243 offset:4096
	ds_read_b128 v[64:67], v243 offset:6144
	ds_read_b128 v[120:123], v242
	ds_read_b128 v[88:91], v242 offset:2048
	ds_read_b128 v[84:87], v242 offset:4096
	ds_read_b128 v[68:71], v242 offset:6144
	v_add3_u32 v242, s4, v104, v107
	v_add3_u32 v243, s4, v105, v107
	s_xor_b32 s30, s30, 1
	s_lshl_b32 s31, s30, 16
	v_readfirstlane_b32 s98, v102
	v_readfirstlane_b32 s99, v110
	v_readfirstlane_b32 s100, v103
	s_add_u32 s98, s98, s4
	s_add_u32 s99, s99, s4
	s_add_u32 s100, s100, s4
	s_sub_u32 vcc_lo, s31, s4
	s_add_u32 s98, s98, vcc_lo
	s_add_u32 s99, s99, vcc_lo
	s_add_u32 s100, s100, vcc_lo
	s_mov_b32 m0, s98
	s_nop 0
	global_load_lds_dwordx4 v[98:99], off
	s_add_u32 m0, s98, 0x400
	v_lshl_add_u64 v[254:255], v[98:99], 0, s[8:9]
	global_load_lds_dwordx4 v[254:255], off
	s_add_u32 m0, s99, 0x8000
	s_nop 0
	global_load_lds_dwordx4 v[96:97], off
	s_add_u32 m0, s100, 0x8400
	v_lshl_add_u64 v[254:255], v[96:97], 0, s[8:9]
	global_load_lds_dwordx4 v[254:255], off
	s_add_u32 m0, s100, 0x8800
	v_lshl_add_u64 v[254:255], v[96:97], 0, s[10:11]
	global_load_lds_dwordx4 v[254:255], off
	s_add_u32 m0, s100, 0x8c00
	v_lshl_add_u64 v[254:255], v[96:97], 0, s[12:13]
	global_load_lds_dwordx4 v[254:255], off
	s_sub_u32 s98, s98, vcc_lo
	s_sub_u32 s99, s99, vcc_lo
	s_sub_u32 s100, s100, vcc_lo
	s_mov_b64 s[4:5], 0x80
	v_lshl_add_u64 v[98:99], v[98:99], 0, s[4:5]
	v_lshl_add_u64 v[96:97], v[96:97], 0, s[4:5]
	s_branch .Lg4_3_mid

;     ...
;   for (int kt = 0; kt < nk; ++kt) {
;     const bool issue = kt + 1 < nk;
;     const int ibuf = buf ^ 1;
; #pragma unroll
;     for (int s2 = 0; s2 < 2; ++s2) {
;       bf16x8 bf[4], af[MF];
;       {
;         const unsigned la = lds_base + buf * 65536 + ((wm * MF) << 11) + (s2 ? lofs1 : lofs0);
;         const unsigned lb = lds_base + buf * 65536 + 32768 + ((wn * 4) << 11) + (s2 ? lofs1 : lofs0);
;         if constexpr (MF == 8) {
;           asm volatile(
;               "ds_read_b128 %0, %13\n\tds_read_b128 %1, %13 offset:2048\n\tds_read_b128 %2, %13 offset:4096\n\tds_read_b128 %3, %13 offset:6144\n\t"
;               "ds_read_b128 %4, %12\n\tds_read_b128 %5, %12 offset:2048\n\tds_read_b128 %6, %12 offset:4096\n\tds_read_b128 %7, %12 offset:6144\n\t"
;               "ds_read_b128 %8, %12 offset:8192\n\tds_read_b128 %9, %12 offset:10240\n\tds_read_b128 %10, %12 offset:12288\n\tds_read_b128 %11, %12 offset:14336\n\t"
;               "s_waitcnt lgkmcnt(0)"
;               : "=&v"(bf[0]), "=&v"(bf[1]), "=&v"(bf[2]), "=&v"(bf[3]), "=&v"(af[0]), "=&v"(af[1]), "=&v"(af[2]), "=&v"(af[3]),
;                 "=&v"(af[4]), "=&v"(af[5]), "=&v"(af[6]), "=&v"(af[7])
;               : "v"(la), "v"(lb)
;               : "memory");
;         } else {
;           asm volatile(
;               "ds_read_b128 %0, %9\n\tds_read_b128 %1, %9 offset:2048\n\tds_read_b128 %2, %9 offset:4096\n\tds_read_b128 %3, %9 offset:6144\n\t"
;               "ds_read_b128 %4, %8\n\tds_read_b128 %5, %8 offset:2048\n\tds_read_b128 %6, %8 offset:4096\n\tds_read_b128 %7, %8 offset:6144\n\t"
;               "s_waitcnt lgkmcnt(0)"
;               : "=&v"(bf[0]), "=&v"(bf[1]), "=&v"(bf[2]), "=&v"(bf[3]), "=&v"(af[0]), "=&v"(af[1]), "=&v"(af[2]), "=&v"(af[3])
;               : "v"(la), "v"(lb)
;               : "memory");
;         }
;       }
;       __builtin_amdgcn_sched_barrier(0);
;       __builtin_amdgcn_s_setprio(1);
; #pragma unroll
;       for (int m = 0; m < MF; ++m) {
; #pragma unroll
;         for (int n = 0; n < 4; ++n) acc[m][n] = mfma16(bf[n], af[m], acc[m][n]);
;         if constexpr (MF == 8) {
;           if (m & 1) {
;             __builtin_amdgcn_sched_barrier(0);
;             if (issue) {
;               if (s2 == 0) { if (m == 1) GEMM_PIECE_A(ibuf, 0); if (m == 3) GEMM_PIECE_A(ibuf, 1); if (m == 5) GEMM_PIECE_A(ibuf, 2); if (m == 7) GEMM_PIECE_A(ibuf, 3); }
.LBB0_924:
	s_mov_b32 s2, s54
	s_cmp_gt_u32 s5, 2
	s_cselect_b64 s[0:1], -1, 0
	s_lshl_b32 s2, s2, 16
	v_add3_u32 v242, s2, v104, v106
	v_add3_u32 v243, s2, v105, v106
	ds_read_b128 v[80:83], v243
	ds_read_b128 v[76:79], v243 offset:2048
	ds_read_b128 v[72:75], v243 offset:4096
	ds_read_b128 v[64:67], v243 offset:6144
	ds_read_b128 v[120:123], v242
	ds_read_b128 v[88:91], v242 offset:2048
	ds_read_b128 v[84:87], v242 offset:4096
	ds_read_b128 v[68:71], v242 offset:6144
	v_add3_u32 v242, s2, v104, v107
	v_add3_u32 v243, s2, v105, v107
	s_xor_b32 s54, s54, 1
	s_lshl_b32 s55, s54, 16
	v_readfirstlane_b32 s98, v102
	v_readfirstlane_b32 s99, v110
	v_readfirstlane_b32 s100, v103
	s_add_u32 s98, s98, s2
	s_add_u32 s99, s99, s2
	s_add_u32 s100, s100, s2
	s_setprio 1
	v_mfma_f32_16x16x32_bf16 v[60:63], v[208:211], v[224:227], v[60:63]
	v_mfma_f32_16x16x32_bf16 v[56:59], v[212:215], v[224:227], v[56:59]
	v_mfma_f32_16x16x32_bf16 v[52:55], v[216:219], v[224:227], v[52:55]
	v_mfma_f32_16x16x32_bf16 v[48:51], v[220:223], v[224:227], v[48:51]
	v_mfma_f32_16x16x32_bf16 v[44:47], v[208:211], v[228:231], v[44:47]
	v_mfma_f32_16x16x32_bf16 v[40:43], v[212:215], v[228:231], v[40:43]
	v_mfma_f32_16x16x32_bf16 v[36:39], v[216:219], v[228:231], v[36:39]
	v_mfma_f32_16x16x32_bf16 v[32:35], v[220:223], v[228:231], v[32:35]
	v_mfma_f32_16x16x32_bf16 v[28:31], v[208:211], v[232:235], v[28:31]
	v_mfma_f32_16x16x32_bf16 v[24:27], v[212:215], v[232:235], v[24:27]
	v_mfma_f32_16x16x32_bf16 v[20:23], v[216:219], v[232:235], v[20:23]
	v_mfma_f32_16x16x32_bf16 v[16:19], v[220:223], v[232:235], v[16:19]
	v_mfma_f32_16x16x32_bf16 v[0:3], v[208:211], v[238:241], v[0:3]
	v_mfma_f32_16x16x32_bf16 v[4:7], v[212:215], v[238:241], v[4:7]
	v_mfma_f32_16x16x32_bf16 v[8:11], v[216:219], v[238:241], v[8:11]
	v_mfma_f32_16x16x32_bf16 v[12:15], v[220:223], v[238:241], v[12:15]
	s_setprio 0
.Lg4_4_mid:
	s_waitcnt lgkmcnt(0)
	ds_read_b128 v[208:211], v243
	ds_read_b128 v[212:215], v243 offset:2048
	ds_read_b128 v[216:219], v243 offset:4096
	ds_read_b128 v[220:223], v243 offset:6144
	ds_read_b128 v[224:227], v242
	ds_read_b128 v[228:231], v242 offset:2048
	ds_read_b128 v[232:235], v242 offset:4096
	ds_read_b128 v[238:241], v242 offset:6144
	s_setprio 1
	v_mfma_f32_16x16x32_bf16 v[60:63], v[80:83], v[120:123], v[60:63]
	v_mfma_f32_16x16x32_bf16 v[56:59], v[76:79], v[120:123], v[56:59]
	v_mfma_f32_16x16x32_bf16 v[52:55], v[72:75], v[120:123], v[52:55]
	v_mfma_f32_16x16x32_bf16 v[48:51], v[64:67], v[120:123], v[48:51]
	v_mfma_f32_16x16x32_bf16 v[44:47], v[80:83], v[88:91], v[44:47]
	v_mfma_f32_16x16x32_bf16 v[40:43], v[76:79], v[88:91], v[40:43]
	v_mfma_f32_16x16x32_bf16 v[36:39], v[72:75], v[88:91], v[36:39]
	v_mfma_f32_16x16x32_bf16 v[32:35], v[64:67], v[88:91], v[32:35]
	s_setprio 0
	s_waitcnt lgkmcnt(0)
	s_barrier
	s_cmp_eq_u64 s[0:1], 0
	s_cbranch_scc1 .Lg4_4_nodma
	s_setprio 1
	v_mfma_f32_16x16x32_bf16 v[28:31], v[80:83], v[84:87], v[28:31]
	s_mov_b32 m0, s98
	s_nop 0
	global_load_lds_dwordx4 v[96:97], off
	v_mfma_f32_16x16x32_bf16 v[24:27], v[76:79], v[84:87], v[24:27]
	s_add_u32 m0, s98, 0x400
	v_lshl_add_u64 v[254:255], v[96:97], 0, s[10:11]
	global_load_lds_dwordx4 v[254:255], off
	v_mfma_f32_16x16x32_bf16 v[20:23], v[72:75], v[84:87], v[20:23]
	s_add_u32 m0, s99, 0x8000
	s_nop 0
	global_load_lds_dwordx4 v[98:99], off
	v_mfma_f32_16x16x32_bf16 v[16:19], v[64:67], v[84:87], v[16:19]
	s_add_u32 m0, s100, 0x8400
	v_lshl_add_u64 v[254:255], v[98:99], 0, s[10:11]
	global_load_lds_dwordx4 v[254:255], off
	v_mfma_f32_16x16x32_bf16 v[0:3], v[80:83], v[68:71], v[0:3]
	s_add_u32 m0, s100, 0x8800
	v_lshl_add_u64 v[254:255], v[98:99], 0, s[12:13]
	global_load_lds_dwordx4 v[254:255], off
	v_mfma_f32_16x16x32_bf16 v[4:7], v[76:79], v[68:71], v[4:7]
	s_add_u32 m0, s100, 0x8c00
	v_lshl_add_u64 v[254:255], v[98:99], 0, s[24:25]
	global_load_lds_dwordx4 v[254:255], off
	v_mfma_f32_16x16x32_bf16 v[8:11], v[72:75], v[68:71], v[8:11]
	v_mfma_f32_16x16x32_bf16 v[12:15], v[64:67], v[68:71], v[12:15]
	s_setprio 0
	s_mov_b64 s[0:1], 0x80
	s_waitcnt vmcnt(6)
	s_branch .LBB0_923
;     ...
;   if (preloaded) { ag += 64; bg += 64; }
;   else GEMM_STAGE(0);
;   GEMM_WAIT0;
;   int buf = 0;
; #pragma unroll 1
;   for (int kt = 0; kt < nk; ++kt) {
;     const bool issue = kt + 1 < nk;
;     const int ibuf = buf ^ 1;
; #pragma unroll
;     for (int s2 = 0; s2 < 2; ++s2) {
;       bf16x8 bf[4], af[MF];
;       {
;         const unsigned la = lds_base + buf * 65536 + ((wm * MF) << 11) + (s2 ? lofs1 : lofs0);
;         const unsigned lb = lds_base + buf * 65536 + 32768 + ((wn * 4) << 11) + (s2 ? lofs1 : lofs0);
;         if constexpr (MF == 8) {
;           asm volatile(
;               "ds_read_b128 %0, %13\n\tds_read_b128 %1, %13 offset:2048\n\tds_read_b128 %2, %13 offset:4096\n\tds_read_b128 %3, %13 offset:6144\n\t"
;               "ds_read_b128 %4, %12\n\tds_read_b128 %5, %12 offset:2048\n\tds_read_b128 %6, %12 offset:4096\n\tds_read_b128 %7, %12 offset:6144\n\t"
;               "ds_read_b128 %8, %12 offset:8192\n\tds_read_b128 %9, %12 offset:10240\n\tds_read_b128 %10, %12 offset:12288\n\tds_read_b128 %11, %12 offset:14336\n\t"
;               "s_waitcnt lgkmcnt(0)"
;               : "=&v"(bf[0]), "=&v"(bf[1]), "=&v"(bf[2]), "=&v"(bf[3]), "=&v"(af[0]), "=&v"(af[1]), "=&v"(af[2]), "=&v"(af[3]),
;                 "=&v"(af[4]), "=&v"(af[5]), "=&v"(af[6]), "=&v"(af[7])
;               : "v"(la), "v"(lb)
;               : "memory");
;         } else {
;           asm volatile(
;               "ds_read_b128 %0, %9\n\tds_read_b128 %1, %9 offset:2048\n\tds_read_b128 %2, %9 offset:4096\n\tds_read_b128 %3, %9 offset:6144\n\t"
;               "ds_read_b128 %4, %8\n\tds_read_b128 %5, %8 offset:2048\n\tds_read_b128 %6, %8 offset:4096\n\tds_read_b128 %7, %8 offset:6144\n\t"
;               "s_waitcnt lgkmcnt(0)"
;               : "=&v"(bf[0]), "=&v"(bf[1]), "=&v"(bf[2]), "=&v"(bf[3]), "=&v"(af[0]), "=&v"(af[1]), "=&v"(af[2]), "=&v"(af[3])
;               : "v"(la), "v"(lb)
;               : "memory");
;         }
;       }
;       __builtin_amdgcn_sched_barrier(0);
;       __builtin_amdgcn_s_setprio(1);
; #pragma unroll
;       for (int m = 0; m < MF; ++m) {
; #pragma unroll
;         for (int n = 0; n < 4; ++n) acc[m][n] = mfma16(bf[n], af[m], acc[m][n]);
;         if constexpr (MF == 8) {
;           if (m & 1) {
;             __builtin_amdgcn_sched_barrier(0);
;             if (issue) {
.Lg4_4_nodma:
	s_setprio 1
	v_mfma_f32_16x16x32_bf16 v[28:31], v[80:83], v[84:87], v[28:31]
	v_mfma_f32_16x16x32_bf16 v[24:27], v[76:79], v[84:87], v[24:27]
	v_mfma_f32_16x16x32_bf16 v[20:23], v[72:75], v[84:87], v[20:23]
	v_mfma_f32_16x16x32_bf16 v[16:19], v[64:67], v[84:87], v[16:19]
	v_mfma_f32_16x16x32_bf16 v[0:3], v[80:83], v[68:71], v[0:3]
	v_mfma_f32_16x16x32_bf16 v[4:7], v[76:79], v[68:71], v[4:7]
	v_mfma_f32_16x16x32_bf16 v[8:11], v[72:75], v[68:71], v[8:11]
	v_mfma_f32_16x16x32_bf16 v[12:15], v[64:67], v[68:71], v[12:15]
	s_setprio 0
	s_mov_b64 s[0:1], 0
	s_waitcnt vmcnt(0)
	s_branch .LBB0_923
.Lg4_4_entry:
	s_mov_b32 s2, s54
	s_cmp_gt_u32 s5, 2
	s_cselect_b64 s[0:1], -1, 0
	s_lshl_b32 s2, s2, 16
	v_add3_u32 v242, s2, v104, v106
	v_add3_u32 v243, s2, v105, v106
	ds_read_b128 v[80:83], v243
	ds_read_b128 v[76:79], v243 offset:2048
	ds_read_b128 v[72:75], v243 offset:4096
	ds_read_b128 v[64:67], v243 offset:6144
	ds_read_b128 v[120:123], v242
	ds_read_b128 v[88:91], v242 offset:2048
	ds_read_b128 v[84:87], v242 offset:4096
	ds_read_b128 v[68:71], v242 offset:6144
	v_add3_u32 v242, s2, v104, v107
	v_add3_u32 v243, s2, v105, v107
	s_xor_b32 s54, s54, 1
	s_lshl_b32 s55, s54, 16
	v_readfirstlane_b32 s98, v102
	v_readfirstlane_b32 s99, v110
	v_readfirstlane_b32 s100, v103
	s_add_u32 s98, s98, s2
	s_add_u32 s99, s99, s2
	s_add_u32 s100, s100, s2
	s_sub_u32 vcc_lo, s55, s2
	s_add_u32 s98, s98, vcc_lo
	s_add_u32 s99, s99, vcc_lo
	s_add_u32 s100, s100, vcc_lo
	s_mov_b32 m0, s98
	s_nop 0
	global_load_lds_dwordx4 v[96:97], off
	s_add_u32 m0, s98, 0x400
	v_lshl_add_u64 v[254:255], v[96:97], 0, s[10:11]
	global_load_lds_dwordx4 v[254:255], off
	s_add_u32 m0, s99, 0x8000
	s_nop 0
	global_load_lds_dwordx4 v[98:99], off
	s_add_u32 m0, s100, 0x8400
	v_lshl_add_u64 v[254:255], v[98:99], 0, s[10:11]
	global_load_lds_dwordx4 v[254:255], off
	s_add_u32 m0, s100, 0x8800
	v_lshl_add_u64 v[254:255], v[98:99], 0, s[12:13]
	global_load_lds_dwordx4 v[254:255], off
	s_add_u32 m0, s100, 0x8c00
	v_lshl_add_u64 v[254:255], v[98:99], 0, s[24:25]
	global_load_lds_dwordx4 v[254:255], off
	s_sub_u32 s98, s98, vcc_lo
	s_sub_u32 s99, s99, vcc_lo
	s_sub_u32 s100, s100, vcc_lo
	s_mov_b64 s[0:1], 0x80
	v_lshl_add_u64 v[96:97], v[96:97], 0, s[0:1]
	v_lshl_add_u64 v[98:99], v[98:99], 0, s[0:1]
	s_branch .Lg4_4_mid
.Lg4_4_exit:
	s_setprio 1
	v_mfma_f32_16x16x32_bf16 v[60:63], v[208:211], v[224:227], v[60:63]
	v_mfma_f32_16x16x32_bf16 v[56:59], v[212:215], v[224:227], v[56:59]
	v_mfma_f32_16x16x32_bf16 v[52:55], v[216:219], v[224:227], v[52:55]
	v_mfma_f32_16x16x32_bf16 v[48:51], v[220:223], v[224:227], v[48:51]
	v_mfma_f32_16x16x32_bf16 v[44:47], v[208:211], v[228:231], v[44:47]
	v_mfma_f32_16x16x32_bf16 v[40:43], v[212:215], v[228:231], v[40:43]
	v_mfma_f32_16x16x32_bf16 v[36:39], v[216:219], v[228:231], v[36:39]
	v_mfma_f32_16x16x32_bf16 v[32:35], v[220:223], v[228:231], v[32:35]
	v_mfma_f32_16x16x32_bf16 v[28:31], v[208:211], v[232:235], v[28:31]
	v_mfma_f32_16x16x32_bf16 v[24:27], v[212:215], v[232:235], v[24:27]
	v_mfma_f32_16x16x32_bf16 v[20:23], v[216:219], v[232:235], v[20:23]
	v_mfma_f32_16x16x32_bf16 v[16:19], v[220:223], v[232:235], v[16:19]
	v_mfma_f32_16x16x32_bf16 v[0:3], v[208:211], v[238:241], v[0:3]
	v_mfma_f32_16x16x32_bf16 v[4:7], v[212:215], v[238:241], v[4:7]
	v_mfma_f32_16x16x32_bf16 v[8:11], v[216:219], v[238:241], v[8:11]
	v_mfma_f32_16x16x32_bf16 v[12:15], v[220:223], v[238:241], v[12:15]
	s_setprio 0
	s_nop 7
	s_nop 3
	s_branch .LBB0_936

;     ...
;   for (int kt = 0; kt < nk; ++kt) {
;     const bool issue = kt + 1 < nk;
;     const int ibuf = buf ^ 1;
; #pragma unroll
;     for (int s2 = 0; s2 < 2; ++s2) {
;       bf16x8 bf[4], af[MF];
;       {
;         const unsigned la = lds_base + buf * 65536 + ((wm * MF) << 11) + (s2 ? lofs1 : lofs0);
;         const unsigned lb = lds_base + buf * 65536 + 32768 + ((wn * 4) << 11) + (s2 ? lofs1 : lofs0);
;         if constexpr (MF == 8) {
;           asm volatile(
;               "ds_read_b128 %0, %13\n\tds_read_b128 %1, %13 offset:2048\n\tds_read_b128 %2, %13 offset:4096\n\tds_read_b128 %3, %13 offset:6144\n\t"
;               "ds_read_b128 %4, %12\n\tds_read_b128 %5, %12 offset:2048\n\tds_read_b128 %6, %12 offset:4096\n\tds_read_b128 %7, %12 offset:6144\n\t"
;               "ds_read_b128 %8, %12 offset:8192\n\tds_read_b128 %9, %12 offset:10240\n\tds_read_b128 %10, %12 offset:12288\n\tds_read_b128 %11, %12 offset:14336\n\t"
;               "s_waitcnt lgkmcnt(0)"
;               : "=&v"(bf[0]), "=&v"(bf[1]), "=&v"(bf[2]), "=&v"(bf[3]), "=&v"(af[0]), "=&v"(af[1]), "=&v"(af[2]), "=&v"(af[3]),
;                 "=&v"(af[4]), "=&v"(af[5]), "=&v"(af[6]), "=&v"(af[7])
;               : "v"(la), "v"(lb)
;               : "memory");
;         } else {
;           asm volatile(
;               "ds_read_b128 %0, %9\n\tds_read_b128 %1, %9 offset:2048\n\tds_read_b128 %2, %9 offset:4096\n\tds_read_b128 %3, %9 offset:6144\n\t"
;               "ds_read_b128 %4, %8\n\tds_read_b128 %5, %8 offset:2048\n\tds_read_b128 %6, %8 offset:4096\n\tds_read_b128 %7, %8 offset:6144\n\t"
;               "s_waitcnt lgkmcnt(0)"
;               : "=&v"(bf[0]), "=&v"(bf[1]), "=&v"(bf[2]), "=&v"(bf[3]), "=&v"(af[0]), "=&v"(af[1]), "=&v"(af[2]), "=&v"(af[3])
;               : "v"(la), "v"(lb)
;               : "memory");
;         }
;       }
;       __builtin_amdgcn_sched_barrier(0);
;       __builtin_amdgcn_s_setprio(1);
; #pragma unroll
;       for (int m = 0; m < MF; ++m) {
; #pragma unroll
;         for (int n = 0; n < 4; ++n) acc[m][n] = mfma16(bf[n], af[m], acc[m][n]);
;         if constexpr (MF == 8) {
;           if (m & 1) {
;             __builtin_amdgcn_sched_barrier(0);
;             if (issue) {
;               if (s2 == 0) { if (m == 1) GEMM_PIECE_A(ibuf, 0); if (m == 3) GEMM_PIECE_A(ibuf, 1); if (m == 5) GEMM_PIECE_A(ibuf, 2); if (m == 7) GEMM_PIECE_A(ibuf, 3); }
.LBB0_983:
	s_mov_b32 s2, s51
	s_cmp_gt_u32 s5, 2
	s_cselect_b64 s[0:1], -1, 0
	s_lshl_b32 s2, s2, 16
	v_add3_u32 v242, s2, v104, v106
	v_add3_u32 v243, s2, v105, v106
	ds_read_b128 v[80:83], v243
	ds_read_b128 v[76:79], v243 offset:2048
	ds_read_b128 v[72:75], v243 offset:4096
	ds_read_b128 v[64:67], v243 offset:6144
	ds_read_b128 v[120:123], v242
	ds_read_b128 v[88:91], v242 offset:2048
	ds_read_b128 v[84:87], v242 offset:4096
	ds_read_b128 v[68:71], v242 offset:6144
	v_add3_u32 v242, s2, v104, v107
	v_add3_u32 v243, s2, v105, v107
	s_xor_b32 s51, s51, 1
	s_lshl_b32 s52, s51, 16
	v_readfirstlane_b32 s98, v102
	v_readfirstlane_b32 s99, v110
	v_readfirstlane_b32 s100, v103
	s_add_u32 s98, s98, s2
	s_add_u32 s99, s99, s2
	s_add_u32 s100, s100, s2
	s_setprio 1
	v_mfma_f32_16x16x32_bf16 v[60:63], v[208:211], v[224:227], v[60:63]
	v_mfma_f32_16x16x32_bf16 v[56:59], v[212:215], v[224:227], v[56:59]
	v_mfma_f32_16x16x32_bf16 v[52:55], v[216:219], v[224:227], v[52:55]
	v_mfma_f32_16x16x32_bf16 v[48:51], v[220:223], v[224:227], v[48:51]
	v_mfma_f32_16x16x32_bf16 v[44:47], v[208:211], v[228:231], v[44:47]
	v_mfma_f32_16x16x32_bf16 v[40:43], v[212:215], v[228:231], v[40:43]
	v_mfma_f32_16x16x32_bf16 v[36:39], v[216:219], v[228:231], v[36:39]
	v_mfma_f32_16x16x32_bf16 v[32:35], v[220:223], v[228:231], v[32:35]
	v_mfma_f32_16x16x32_bf16 v[28:31], v[208:211], v[232:235], v[28:31]
	v_mfma_f32_16x16x32_bf16 v[24:27], v[212:215], v[232:235], v[24:27]
	v_mfma_f32_16x16x32_bf16 v[20:23], v[216:219], v[232:235], v[20:23]
	v_mfma_f32_16x16x32_bf16 v[16:19], v[220:223], v[232:235], v[16:19]
	v_mfma_f32_16x16x32_bf16 v[0:3], v[208:211], v[238:241], v[0:3]
	v_mfma_f32_16x16x32_bf16 v[4:7], v[212:215], v[238:241], v[4:7]
	v_mfma_f32_16x16x32_bf16 v[8:11], v[216:219], v[238:241], v[8:11]
	v_mfma_f32_16x16x32_bf16 v[12:15], v[220:223], v[238:241], v[12:15]
	s_setprio 0
.Lg4_5_mid:
	s_waitcnt lgkmcnt(0)
	ds_read_b128 v[208:211], v243
	ds_read_b128 v[212:215], v243 offset:2048
	ds_read_b128 v[216:219], v243 offset:4096
	ds_read_b128 v[220:223], v243 offset:6144
	ds_read_b128 v[224:227], v242
	ds_read_b128 v[228:231], v242 offset:2048
	ds_read_b128 v[232:235], v242 offset:4096
	ds_read_b128 v[238:241], v242 offset:6144
	s_setprio 1
	v_mfma_f32_16x16x32_bf16 v[60:63], v[80:83], v[120:123], v[60:63]
	v_mfma_f32_16x16x32_bf16 v[56:59], v[76:79], v[120:123], v[56:59]
	v_mfma_f32_16x16x32_bf16 v[52:55], v[72:75], v[120:123], v[52:55]
	v_mfma_f32_16x16x32_bf16 v[48:51], v[64:67], v[120:123], v[48:51]
	v_mfma_f32_16x16x32_bf16 v[44:47], v[80:83], v[88:91], v[44:47]
	v_mfma_f32_16x16x32_bf16 v[40:43], v[76:79], v[88:91], v[40:43]
	v_mfma_f32_16x16x32_bf16 v[36:39], v[72:75], v[88:91], v[36:39]
	v_mfma_f32_16x16x32_bf16 v[32:35], v[64:67], v[88:91], v[32:35]
	s_setprio 0
	s_waitcnt lgkmcnt(0)
	s_barrier
	s_cmp_eq_u64 s[0:1], 0
	s_cbranch_scc1 .Lg4_5_nodma
	s_setprio 1
	v_mfma_f32_16x16x32_bf16 v[28:31], v[80:83], v[84:87], v[28:31]
	s_mov_b32 m0, s98
	s_nop 0
	global_load_lds_dwordx4 v[96:97], off
	v_mfma_f32_16x16x32_bf16 v[24:27], v[76:79], v[84:87], v[24:27]
	s_add_u32 m0, s98, 0x400
	v_lshl_add_u64 v[254:255], v[96:97], 0, s[10:11]
	global_load_lds_dwordx4 v[254:255], off
	v_mfma_f32_16x16x32_bf16 v[20:23], v[72:75], v[84:87], v[20:23]
	s_add_u32 m0, s99, 0x8000
	s_nop 0
	global_load_lds_dwordx4 v[98:99], off
	v_mfma_f32_16x16x32_bf16 v[16:19], v[64:67], v[84:87], v[16:19]
	s_add_u32 m0, s100, 0x8400
	v_lshl_add_u64 v[254:255], v[98:99], 0, s[10:11]
	global_load_lds_dwordx4 v[254:255], off
	v_mfma_f32_16x16x32_bf16 v[0:3], v[80:83], v[68:71], v[0:3]
	s_add_u32 m0, s100, 0x8800
	v_lshl_add_u64 v[254:255], v[98:99], 0, s[12:13]
	global_load_lds_dwordx4 v[254:255], off
	v_mfma_f32_16x16x32_bf16 v[4:7], v[76:79], v[68:71], v[4:7]
	s_add_u32 m0, s100, 0x8c00
	v_lshl_add_u64 v[254:255], v[98:99], 0, s[18:19]
	global_load_lds_dwordx4 v[254:255], off
	v_mfma_f32_16x16x32_bf16 v[8:11], v[72:75], v[68:71], v[8:11]
	v_mfma_f32_16x16x32_bf16 v[12:15], v[64:67], v[68:71], v[12:15]
	s_setprio 0
	s_mov_b64 s[0:1], 0x80
	s_waitcnt vmcnt(6)
	s_branch .LBB0_982

; #define GEMM_STAGE(BUF)                                                    \
;   do {                                                                     \
;     _Pragma("unroll") for (int i = 0; i < APW; ++i) GEMM_PIECE_A(BUF, i);  \
;     _Pragma("unroll") for (int i = 0; i < 4; ++i) GEMM_PIECE_B(BUF, i);    \
;     ag += 64; bg += 64;                                                    \
;   } while (0)
;     ...
;   if (preloaded) { ag += 64; bg += 64; }
;   else GEMM_STAGE(0);
;   GEMM_WAIT0;
;   int buf = 0;
; #pragma unroll 1
;   for (int kt = 0; kt < nk; ++kt) {
;     const bool issue = kt + 1 < nk;
;     const int ibuf = buf ^ 1;
; #pragma unroll
;     for (int s2 = 0; s2 < 2; ++s2) {
;       bf16x8 bf[4], af[MF];
;       {
;         const unsigned la = lds_base + buf * 65536 + ((wm * MF) << 11) + (s2 ? lofs1 : lofs0);
;         const unsigned lb = lds_base + buf * 65536 + 32768 + ((wn * 4) << 11) + (s2 ? lofs1 : lofs0);
;         if constexpr (MF == 8) {
;           asm volatile(
;               "ds_read_b128 %0, %13\n\tds_read_b128 %1, %13 offset:2048\n\tds_read_b128 %2, %13 offset:4096\n\tds_read_b128 %3, %13 offset:6144\n\t"
;               "ds_read_b128 %4, %12\n\tds_read_b128 %5, %12 offset:2048\n\tds_read_b128 %6, %12 offset:4096\n\tds_read_b128 %7, %12 offset:6144\n\t"
;               "ds_read_b128 %8, %12 offset:8192\n\tds_read_b128 %9, %12 offset:10240\n\tds_read_b128 %10, %12 offset:12288\n\tds_read_b128 %11, %12 offset:14336\n\t"
;               "s_waitcnt lgkmcnt(0)"
;               : "=&v"(bf[0]), "=&v"(bf[1]), "=&v"(bf[2]), "=&v"(bf[3]), "=&v"(af[0]), "=&v"(af[1]), "=&v"(af[2]), "=&v"(af[3]),
;                 "=&v"(af[4]), "=&v"(af[5]), "=&v"(af[6]), "=&v"(af[7])
;               : "v"(la), "v"(lb)
;               : "memory");
;         } else {
;           asm volatile(
;               "ds_read_b128 %0, %9\n\tds_read_b128 %1, %9 offset:2048\n\tds_read_b128 %2, %9 offset:4096\n\tds_read_b128 %3, %9 offset:6144\n\t"
;               "ds_read_b128 %4, %8\n\tds_read_b128 %5, %8 offset:2048\n\tds_read_b128 %6, %8 offset:4096\n\tds_read_b128 %7, %8 offset:6144\n\t"
;               "s_waitcnt lgkmcnt(0)"
;               : "=&v"(bf[0]), "=&v"(bf[1]), "=&v"(bf[2]), "=&v"(bf[3]), "=&v"(af[0]), "=&v"(af[1]), "=&v"(af[2]), "=&v"(af[3])
;               : "v"(la), "v"(lb)
;               : "memory");
;         }
;       }
.Lg4_5_entry:
	s_mov_b32 s2, s51
	s_cmp_gt_u32 s5, 2
	s_cselect_b64 s[0:1], -1, 0
	s_lshl_b32 s2, s2, 16
	v_add3_u32 v242, s2, v104, v106
	v_add3_u32 v243, s2, v105, v106
	ds_read_b128 v[80:83], v243
	ds_read_b128 v[76:79], v243 offset:2048
	ds_read_b128 v[72:75], v243 offset:4096
	ds_read_b128 v[64:67], v243 offset:6144
	ds_read_b128 v[120:123], v242
	ds_read_b128 v[88:91], v242 offset:2048
	ds_read_b128 v[84:87], v242 offset:4096
	ds_read_b128 v[68:71], v242 offset:6144
	v_add3_u32 v242, s2, v104, v107
	v_add3_u32 v243, s2, v105, v107
	s_xor_b32 s51, s51, 1
	s_lshl_b32 s52, s51, 16
	v_readfirstlane_b32 s98, v102
	v_readfirstlane_b32 s99, v110
	v_readfirstlane_b32 s100, v103
	s_add_u32 s98, s98, s2
	s_add_u32 s99, s99, s2
	s_add_u32 s100, s100, s2
	s_sub_u32 vcc_lo, s52, s2
	s_add_u32 s98, s98, vcc_lo
	s_add_u32 s99, s99, vcc_lo
	s_add_u32 s100, s100, vcc_lo
	s_mov_b32 m0, s98
	s_nop 0
	global_load_lds_dwordx4 v[96:97], off
	s_add_u32 m0, s98, 0x400
	v_lshl_add_u64 v[254:255], v[96:97], 0, s[10:11]
	global_load_lds_dwordx4 v[254:255], off
	s_add_u32 m0, s99, 0x8000
	s_nop 0
	global_load_lds_dwordx4 v[98:99], off
	s_add_u32 m0, s100, 0x8400
	v_lshl_add_u64 v[254:255], v[98:99], 0, s[10:11]
	global_load_lds_dwordx4 v[254:255], off
	s_add_u32 m0, s100, 0x8800
	v_lshl_add_u64 v[254:255], v[98:99], 0, s[12:13]
	global_load_lds_dwordx4 v[254:255], off
	s_add_u32 m0, s100, 0x8c00
	v_lshl_add_u64 v[254:255], v[98:99], 0, s[18:19]
	global_load_lds_dwordx4 v[254:255], off
	s_sub_u32 s98, s98, vcc_lo
	s_sub_u32 s99, s99, vcc_lo
	s_sub_u32 s100, s100, vcc_lo
	s_mov_b64 s[0:1], 0x80
	v_lshl_add_u64 v[96:97], v[96:97], 0, s[0:1]
	v_lshl_add_u64 v[98:99], v[98:99], 0, s[0:1]
	s_branch .Lg4_5_mid

;     ...
;   for (int kt = 0; kt < nk; ++kt) {
;     const bool issue = kt + 1 < nk;
;     const int ibuf = buf ^ 1;
; #pragma unroll
;     for (int s2 = 0; s2 < 2; ++s2) {
;       bf16x8 bf[4], af[MF];
;       {
;         const unsigned la = lds_base + buf * 65536 + ((wm * MF) << 11) + (s2 ? lofs1 : lofs0);
;         const unsigned lb = lds_base + buf * 65536 + 32768 + ((wn * 4) << 11) + (s2 ? lofs1 : lofs0);
;         if constexpr (MF == 8) {
;           asm volatile(
;               "ds_read_b128 %0, %13\n\tds_read_b128 %1, %13 offset:2048\n\tds_read_b128 %2, %13 offset:4096\n\tds_read_b128 %3, %13 offset:6144\n\t"
;               "ds_read_b128 %4, %12\n\tds_read_b128 %5, %12 offset:2048\n\tds_read_b128 %6, %12 offset:4096\n\tds_read_b128 %7, %12 offset:6144\n\t"
;               "ds_read_b128 %8, %12 offset:8192\n\tds_read_b128 %9, %12 offset:10240\n\tds_read_b128 %10, %12 offset:12288\n\tds_read_b128 %11, %12 offset:14336\n\t"
;               "s_waitcnt lgkmcnt(0)"
;               : "=&v"(bf[0]), "=&v"(bf[1]), "=&v"(bf[2]), "=&v"(bf[3]), "=&v"(af[0]), "=&v"(af[1]), "=&v"(af[2]), "=&v"(af[3]),
;                 "=&v"(af[4]), "=&v"(af[5]), "=&v"(af[6]), "=&v"(af[7])
;               : "v"(la), "v"(lb)
;               : "memory");
;         } else {
;           asm volatile(
;               "ds_read_b128 %0, %9\n\tds_read_b128 %1, %9 offset:2048\n\tds_read_b128 %2, %9 offset:4096\n\tds_read_b128 %3, %9 offset:6144\n\t"
;               "ds_read_b128 %4, %8\n\tds_read_b128 %5, %8 offset:2048\n\tds_read_b128 %6, %8 offset:4096\n\tds_read_b128 %7, %8 offset:6144\n\t"
;               "s_waitcnt lgkmcnt(0)"
;               : "=&v"(bf[0]), "=&v"(bf[1]), "=&v"(bf[2]), "=&v"(bf[3]), "=&v"(af[0]), "=&v"(af[1]), "=&v"(af[2]), "=&v"(af[3])
;               : "v"(la), "v"(lb)
;               : "memory");
;         }
;       }
;       __builtin_amdgcn_sched_barrier(0);
;       __builtin_amdgcn_s_setprio(1);
; #pragma unroll
;       for (int m = 0; m < MF; ++m) {
; #pragma unroll
;         for (int n = 0; n < 4; ++n) acc[m][n] = mfma16(bf[n], af[m], acc[m][n]);
;         if constexpr (MF == 8) {
;           if (m & 1) {
;             __builtin_amdgcn_sched_barrier(0);
;             if (issue) {
;               if (s2 == 0) { if (m == 1) GEMM_PIECE_A(ibuf, 0); if (m == 3) GEMM_PIECE_A(ibuf, 1); if (m == 5) GEMM_PIECE_A(ibuf, 2); if (m == 7) GEMM_PIECE_A(ibuf, 3); }
.LBB0_1767:
	s_add_i32 s31, s31, 1
	s_barrier
	v_lshl_add_u64 v[96:97], v[96:97], 0, s[4:5]
	v_lshl_add_u64 v[98:99], v[98:99], 0, s[4:5]
	s_cmp_eq_u32 s31, 16
	s_cbranch_scc1 .Lg4_6_exit
.LBB0_1768:
	s_mov_b32 s4, s33
	s_cmp_lt_u32 s31, 14
	s_cselect_b64 s[24:25], -1, 0
	s_lshl_b32 s4, s4, 16
	v_add3_u32 v242, s4, v104, v106
	v_add3_u32 v243, s4, v105, v106
	ds_read_b128 v[80:83], v243
	ds_read_b128 v[76:79], v243 offset:2048
	ds_read_b128 v[72:75], v243 offset:4096
	ds_read_b128 v[64:67], v243 offset:6144
	ds_read_b128 v[120:123], v242
	ds_read_b128 v[88:91], v242 offset:2048
	ds_read_b128 v[84:87], v242 offset:4096
	ds_read_b128 v[68:71], v242 offset:6144
	v_add3_u32 v242, s4, v104, v107
	v_add3_u32 v243, s4, v105, v107
	s_xor_b32 s33, s33, 1
	s_lshl_b32 s34, s33, 16
	v_readfirstlane_b32 s98, v102
	v_readfirstlane_b32 s99, v110
	v_readfirstlane_b32 s100, v103
	s_add_u32 s98, s98, s4
	s_add_u32 s99, s99, s4
	s_add_u32 s100, s100, s4
	s_setprio 1
	v_mfma_f32_16x16x32_bf16 v[60:63], v[208:211], v[224:227], v[60:63]
	v_mfma_f32_16x16x32_bf16 v[56:59], v[212:215], v[224:227], v[56:59]
	v_mfma_f32_16x16x32_bf16 v[52:55], v[216:219], v[224:227], v[52:55]
	v_mfma_f32_16x16x32_bf16 v[48:51], v[220:223], v[224:227], v[48:51]
	v_mfma_f32_16x16x32_bf16 v[44:47], v[208:211], v[228:231], v[44:47]
	v_mfma_f32_16x16x32_bf16 v[40:43], v[212:215], v[228:231], v[40:43]
	v_mfma_f32_16x16x32_bf16 v[28:31], v[216:219], v[228:231], v[28:31]
	v_mfma_f32_16x16x32_bf16 v[20:23], v[220:223], v[228:231], v[20:23]
	v_mfma_f32_16x16x32_bf16 v[36:39], v[208:211], v[232:235], v[36:39]
	v_mfma_f32_16x16x32_bf16 v[32:35], v[212:215], v[232:235], v[32:35]
	v_mfma_f32_16x16x32_bf16 v[24:27], v[216:219], v[232:235], v[24:27]
	v_mfma_f32_16x16x32_bf16 v[16:19], v[220:223], v[232:235], v[16:19]
	v_mfma_f32_16x16x32_bf16 v[12:15], v[208:211], v[238:241], v[12:15]
	v_mfma_f32_16x16x32_bf16 v[8:11], v[212:215], v[238:241], v[8:11]
	v_mfma_f32_16x16x32_bf16 v[4:7], v[216:219], v[238:241], v[4:7]
	v_mfma_f32_16x16x32_bf16 v[0:3], v[220:223], v[238:241], v[0:3]
	s_setprio 0
.Lg4_6_mid:
	s_waitcnt lgkmcnt(0)
	ds_read_b128 v[208:211], v243
	ds_read_b128 v[212:215], v243 offset:2048
	ds_read_b128 v[216:219], v243 offset:4096
	ds_read_b128 v[220:223], v243 offset:6144
	ds_read_b128 v[224:227], v242
	ds_read_b128 v[228:231], v242 offset:2048
	ds_read_b128 v[232:235], v242 offset:4096
	ds_read_b128 v[238:241], v242 offset:6144
	s_setprio 1
	v_mfma_f32_16x16x32_bf16 v[60:63], v[80:83], v[120:123], v[60:63]
	v_mfma_f32_16x16x32_bf16 v[56:59], v[76:79], v[120:123], v[56:59]
	v_mfma_f32_16x16x32_bf16 v[52:55], v[72:75], v[120:123], v[52:55]
	v_mfma_f32_16x16x32_bf16 v[48:51], v[64:67], v[120:123], v[48:51]
	v_mfma_f32_16x16x32_bf16 v[44:47], v[80:83], v[88:91], v[44:47]
	v_mfma_f32_16x16x32_bf16 v[40:43], v[76:79], v[88:91], v[40:43]
	v_mfma_f32_16x16x32_bf16 v[28:31], v[72:75], v[88:91], v[28:31]
	v_mfma_f32_16x16x32_bf16 v[20:23], v[64:67], v[88:91], v[20:23]
	s_setprio 0
	s_waitcnt lgkmcnt(0)
	s_barrier
	s_cmp_eq_u64 s[24:25], 0
	s_cbranch_scc1 .Lg4_6_nodma
	s_setprio 1
	v_mfma_f32_16x16x32_bf16 v[36:39], v[80:83], v[84:87], v[36:39]
	s_mov_b32 m0, s98
	s_nop 0
	global_load_lds_dwordx4 v[98:99], off
	v_mfma_f32_16x16x32_bf16 v[32:35], v[76:79], v[84:87], v[32:35]
	s_add_u32 m0, s98, 0x400
	v_lshl_add_u64 v[254:255], v[98:99], 0, s[12:13]
	global_load_lds_dwordx4 v[254:255], off
	v_mfma_f32_16x16x32_bf16 v[24:27], v[72:75], v[84:87], v[24:27]
	s_add_u32 m0, s99, 0x8000
	s_nop 0
	global_load_lds_dwordx4 v[96:97], off
	v_mfma_f32_16x16x32_bf16 v[16:19], v[64:67], v[84:87], v[16:19]
	s_add_u32 m0, s100, 0x8400
	v_lshl_add_u64 v[254:255], v[96:97], 0, s[12:13]
	global_load_lds_dwordx4 v[254:255], off
	v_mfma_f32_16x16x32_bf16 v[12:15], v[80:83], v[68:71], v[12:15]
	s_add_u32 m0, s100, 0x8800
	v_lshl_add_u64 v[254:255], v[96:97], 0, s[14:15]
	global_load_lds_dwordx4 v[254:255], off
	v_mfma_f32_16x16x32_bf16 v[8:11], v[76:79], v[68:71], v[8:11]
	s_add_u32 m0, s100, 0x8c00
	v_lshl_add_u64 v[254:255], v[96:97], 0, s[16:17]
	global_load_lds_dwordx4 v[254:255], off
	v_mfma_f32_16x16x32_bf16 v[4:7], v[72:75], v[68:71], v[4:7]
	v_mfma_f32_16x16x32_bf16 v[0:3], v[64:67], v[68:71], v[0:3]
	s_setprio 0
	s_mov_b64 s[4:5], 0x80
	s_waitcnt vmcnt(6)
	s_branch .LBB0_1767

; #define GEMM_STAGE(BUF)                                                    \
;   do {                                                                     \
;     _Pragma("unroll") for (int i = 0; i < APW; ++i) GEMM_PIECE_A(BUF, i);  \
;     _Pragma("unroll") for (int i = 0; i < 4; ++i) GEMM_PIECE_B(BUF, i);    \
;     ag += 64; bg += 64;                                                    \
;   } while (0)
;     ...
;   if (preloaded) { ag += 64; bg += 64; }
;   else GEMM_STAGE(0);
;   GEMM_WAIT0;
;   int buf = 0;
; #pragma unroll 1
;   for (int kt = 0; kt < nk; ++kt) {
;     const bool issue = kt + 1 < nk;
;     const int ibuf = buf ^ 1;
; #pragma unroll
;     for (int s2 = 0; s2 < 2; ++s2) {
;       bf16x8 bf[4], af[MF];
;       {
;         const unsigned la = lds_base + buf * 65536 + ((wm * MF) << 11) + (s2 ? lofs1 : lofs0);
;         const unsigned lb = lds_base + buf * 65536 + 32768 + ((wn * 4) << 11) + (s2 ? lofs1 : lofs0);
;         if constexpr (MF == 8) {
;           asm volatile(
;               "ds_read_b128 %0, %13\n\tds_read_b128 %1, %13 offset:2048\n\tds_read_b128 %2, %13 offset:4096\n\tds_read_b128 %3, %13 offset:6144\n\t"
;               "ds_read_b128 %4, %12\n\tds_read_b128 %5, %12 offset:2048\n\tds_read_b128 %6, %12 offset:4096\n\tds_read_b128 %7, %12 offset:6144\n\t"
;               "ds_read_b128 %8, %12 offset:8192\n\tds_read_b128 %9, %12 offset:10240\n\tds_read_b128 %10, %12 offset:12288\n\tds_read_b128 %11, %12 offset:14336\n\t"
;               "s_waitcnt lgkmcnt(0)"
;               : "=&v"(bf[0]), "=&v"(bf[1]), "=&v"(bf[2]), "=&v"(bf[3]), "=&v"(af[0]), "=&v"(af[1]), "=&v"(af[2]), "=&v"(af[3]),
;                 "=&v"(af[4]), "=&v"(af[5]), "=&v"(af[6]), "=&v"(af[7])
;               : "v"(la), "v"(lb)
;               : "memory");
;         } else {
;           asm volatile(
;               "ds_read_b128 %0, %9\n\tds_read_b128 %1, %9 offset:2048\n\tds_read_b128 %2, %9 offset:4096\n\tds_read_b128 %3, %9 offset:6144\n\t"
;               "ds_read_b128 %4, %8\n\tds_read_b128 %5, %8 offset:2048\n\tds_read_b128 %6, %8 offset:4096\n\tds_read_b128 %7, %8 offset:6144\n\t"
;               "s_waitcnt lgkmcnt(0)"
;               : "=&v"(bf[0]), "=&v"(bf[1]), "=&v"(bf[2]), "=&v"(bf[3]), "=&v"(af[0]), "=&v"(af[1]), "=&v"(af[2]), "=&v"(af[3])
;               : "v"(la), "v"(lb)
;               : "memory");
;         }
;       }
.Lg4_6_entry:
	s_mov_b32 s4, s33
	s_cmp_lt_u32 s31, 14
	s_cselect_b64 s[24:25], -1, 0
	s_lshl_b32 s4, s4, 16
	v_add3_u32 v242, s4, v104, v106
	v_add3_u32 v243, s4, v105, v106
	ds_read_b128 v[80:83], v243
	ds_read_b128 v[76:79], v243 offset:2048
	ds_read_b128 v[72:75], v243 offset:4096
	ds_read_b128 v[64:67], v243 offset:6144
	ds_read_b128 v[120:123], v242
	ds_read_b128 v[88:91], v242 offset:2048
	ds_read_b128 v[84:87], v242 offset:4096
	ds_read_b128 v[68:71], v242 offset:6144
	v_add3_u32 v242, s4, v104, v107
	v_add3_u32 v243, s4, v105, v107
	s_xor_b32 s33, s33, 1
	s_lshl_b32 s34, s33, 16
	v_readfirstlane_b32 s98, v102
	v_readfirstlane_b32 s99, v110
	v_readfirstlane_b32 s100, v103
	s_add_u32 s98, s98, s4
	s_add_u32 s99, s99, s4
	s_add_u32 s100, s100, s4
	s_sub_u32 vcc_lo, s34, s4
	s_add_u32 s98, s98, vcc_lo
	s_add_u32 s99, s99, vcc_lo
	s_add_u32 s100, s100, vcc_lo
	s_mov_b32 m0, s98
	s_nop 0
	global_load_lds_dwordx4 v[98:99], off
	s_add_u32 m0, s98, 0x400
	v_lshl_add_u64 v[254:255], v[98:99], 0, s[12:13]
	global_load_lds_dwordx4 v[254:255], off
	s_add_u32 m0, s99, 0x8000
	s_nop 0
	global_load_lds_dwordx4 v[96:97], off
	s_add_u32 m0, s100, 0x8400
	v_lshl_add_u64 v[254:255], v[96:97], 0, s[12:13]
	global_load_lds_dwordx4 v[254:255], off
	s_add_u32 m0, s100, 0x8800
	v_lshl_add_u64 v[254:255], v[96:97], 0, s[14:15]
	global_load_lds_dwordx4 v[254:255], off
	s_add_u32 m0, s100, 0x8c00
	v_lshl_add_u64 v[254:255], v[96:97], 0, s[16:17]
	global_load_lds_dwordx4 v[254:255], off
	s_sub_u32 s98, s98, vcc_lo
	s_sub_u32 s99, s99, vcc_lo
	s_sub_u32 s100, s100, vcc_lo
	s_mov_b64 s[4:5], 0x80
	v_lshl_add_u64 v[98:99], v[98:99], 0, s[4:5]
	v_lshl_add_u64 v[96:97], v[96:97], 0, s[4:5]
	s_branch .Lg4_6_mid

;     ...
;   for (int kt = 0; kt < nk; ++kt) {
;     const bool issue = kt + 1 < nk;
;     const int ibuf = buf ^ 1;
; #pragma unroll
;     for (int s2 = 0; s2 < 2; ++s2) {
;       bf16x8 bf[4], af[MF];
;       {
;         const unsigned la = lds_base + buf * 65536 + ((wm * MF) << 11) + (s2 ? lofs1 : lofs0);
;         const unsigned lb = lds_base + buf * 65536 + 32768 + ((wn * 4) << 11) + (s2 ? lofs1 : lofs0);
;         if constexpr (MF == 8) {
;           asm volatile(
;               "ds_read_b128 %0, %13\n\tds_read_b128 %1, %13 offset:2048\n\tds_read_b128 %2, %13 offset:4096\n\tds_read_b128 %3, %13 offset:6144\n\t"
;               "ds_read_b128 %4, %12\n\tds_read_b128 %5, %12 offset:2048\n\tds_read_b128 %6, %12 offset:4096\n\tds_read_b128 %7, %12 offset:6144\n\t"
;               "ds_read_b128 %8, %12 offset:8192\n\tds_read_b128 %9, %12 offset:10240\n\tds_read_b128 %10, %12 offset:12288\n\tds_read_b128 %11, %12 offset:14336\n\t"
;               "s_waitcnt lgkmcnt(0)"
;               : "=&v"(bf[0]), "=&v"(bf[1]), "=&v"(bf[2]), "=&v"(bf[3]), "=&v"(af[0]), "=&v"(af[1]), "=&v"(af[2]), "=&v"(af[3]),
;                 "=&v"(af[4]), "=&v"(af[5]), "=&v"(af[6]), "=&v"(af[7])
;               : "v"(la), "v"(lb)
;               : "memory");
;         } else {
;           asm volatile(
;               "ds_read_b128 %0, %9\n\tds_read_b128 %1, %9 offset:2048\n\tds_read_b128 %2, %9 offset:4096\n\tds_read_b128 %3, %9 offset:6144\n\t"
;               "ds_read_b128 %4, %8\n\tds_read_b128 %5, %8 offset:2048\n\tds_read_b128 %6, %8 offset:4096\n\tds_read_b128 %7, %8 offset:6144\n\t"
;               "s_waitcnt lgkmcnt(0)"
;               : "=&v"(bf[0]), "=&v"(bf[1]), "=&v"(bf[2]), "=&v"(bf[3]), "=&v"(af[0]), "=&v"(af[1]), "=&v"(af[2]), "=&v"(af[3])
;               : "v"(la), "v"(lb)
;               : "memory");
;         }
;       }
;       __builtin_amdgcn_sched_barrier(0);
;       __builtin_amdgcn_s_setprio(1);
; #pragma unroll
;       for (int m = 0; m < MF; ++m) {
; #pragma unroll
;         for (int n = 0; n < 4; ++n) acc[m][n] = mfma16(bf[n], af[m], acc[m][n]);
;         if constexpr (MF == 8) {
;           if (m & 1) {
;             __builtin_amdgcn_sched_barrier(0);
;             if (issue) {
;               if (s2 == 0) { if (m == 1) GEMM_PIECE_A(ibuf, 0); if (m == 3) GEMM_PIECE_A(ibuf, 1); if (m == 5) GEMM_PIECE_A(ibuf, 2); if (m == 7) GEMM_PIECE_A(ibuf, 3); }
.LBB0_1812:
	s_add_i32 s28, s28, 1
	s_barrier
	v_lshl_add_u64 v[96:97], v[96:97], 0, s[4:5]
	v_lshl_add_u64 v[98:99], v[98:99], 0, s[4:5]
	s_cmp_eq_u32 s28, 16
	s_cbranch_scc1 .Lg4_7_exit
.LBB0_1813:
	s_mov_b32 s4, s29
	s_cmp_lt_u32 s28, 14
	s_cselect_b64 s[20:21], -1, 0
	s_lshl_b32 s4, s4, 16
	v_add3_u32 v242, s4, v104, v106
	v_add3_u32 v243, s4, v105, v106
	ds_read_b128 v[80:83], v243
	ds_read_b128 v[76:79], v243 offset:2048
	ds_read_b128 v[72:75], v243 offset:4096
	ds_read_b128 v[64:67], v243 offset:6144
	ds_read_b128 v[120:123], v242
	ds_read_b128 v[88:91], v242 offset:2048
	ds_read_b128 v[84:87], v242 offset:4096
	ds_read_b128 v[68:71], v242 offset:6144
	v_add3_u32 v242, s4, v104, v107
	v_add3_u32 v243, s4, v105, v107
	s_xor_b32 s29, s29, 1
	s_lshl_b32 s30, s29, 16
	v_readfirstlane_b32 s98, v102
	v_readfirstlane_b32 s99, v110
	v_readfirstlane_b32 s100, v103
	s_add_u32 s98, s98, s4
	s_add_u32 s99, s99, s4
	s_add_u32 s100, s100, s4
	s_setprio 1
	v_mfma_f32_16x16x32_bf16 v[60:63], v[208:211], v[224:227], v[60:63]
	v_mfma_f32_16x16x32_bf16 v[56:59], v[212:215], v[224:227], v[56:59]
	v_mfma_f32_16x16x32_bf16 v[52:55], v[216:219], v[224:227], v[52:55]
	v_mfma_f32_16x16x32_bf16 v[48:51], v[220:223], v[224:227], v[48:51]
	v_mfma_f32_16x16x32_bf16 v[44:47], v[208:211], v[228:231], v[44:47]
	v_mfma_f32_16x16x32_bf16 v[40:43], v[212:215], v[228:231], v[40:43]
	v_mfma_f32_16x16x32_bf16 v[28:31], v[216:219], v[228:231], v[28:31]
	v_mfma_f32_16x16x32_bf16 v[20:23], v[220:223], v[228:231], v[20:23]
	v_mfma_f32_16x16x32_bf16 v[36:39], v[208:211], v[232:235], v[36:39]
	v_mfma_f32_16x16x32_bf16 v[32:35], v[212:215], v[232:235], v[32:35]
	v_mfma_f32_16x16x32_bf16 v[24:27], v[216:219], v[232:235], v[24:27]
	v_mfma_f32_16x16x32_bf16 v[16:19], v[220:223], v[232:235], v[16:19]
	v_mfma_f32_16x16x32_bf16 v[12:15], v[208:211], v[238:241], v[12:15]
	v_mfma_f32_16x16x32_bf16 v[8:11], v[212:215], v[238:241], v[8:11]
	v_mfma_f32_16x16x32_bf16 v[4:7], v[216:219], v[238:241], v[4:7]
	v_mfma_f32_16x16x32_bf16 v[0:3], v[220:223], v[238:241], v[0:3]
	s_setprio 0

; #define GEMM_STAGE(BUF)                                                    \
;   do {                                                                     \
;     _Pragma("unroll") for (int i = 0; i < APW; ++i) GEMM_PIECE_A(BUF, i);  \
;     _Pragma("unroll") for (int i = 0; i < 4; ++i) GEMM_PIECE_B(BUF, i);    \
;     ag += 64; bg += 64;                                                    \
;   } while (0)
;     ...
;   if (preloaded) { ag += 64; bg += 64; }
;   else GEMM_STAGE(0);
;   GEMM_WAIT0;
;   int buf = 0;
; #pragma unroll 1
;   for (int kt = 0; kt < nk; ++kt) {
;     const bool issue = kt + 1 < nk;
;     const int ibuf = buf ^ 1;
; #pragma unroll
;     for (int s2 = 0; s2 < 2; ++s2) {
;       bf16x8 bf[4], af[MF];
;       {
;         const unsigned la = lds_base + buf * 65536 + ((wm * MF) << 11) + (s2 ? lofs1 : lofs0);
;         const unsigned lb = lds_base + buf * 65536 + 32768 + ((wn * 4) << 11) + (s2 ? lofs1 : lofs0);
;         if constexpr (MF == 8) {
;           asm volatile(
;               "ds_read_b128 %0, %13\n\tds_read_b128 %1, %13 offset:2048\n\tds_read_b128 %2, %13 offset:4096\n\tds_read_b128 %3, %13 offset:6144\n\t"
;               "ds_read_b128 %4, %12\n\tds_read_b128 %5, %12 offset:2048\n\tds_read_b128 %6, %12 offset:4096\n\tds_read_b128 %7, %12 offset:6144\n\t"
;               "ds_read_b128 %8, %12 offset:8192\n\tds_read_b128 %9, %12 offset:10240\n\tds_read_b128 %10, %12 offset:12288\n\tds_read_b128 %11, %12 offset:14336\n\t"
;               "s_waitcnt lgkmcnt(0)"
;               : "=&v"(bf[0]), "=&v"(bf[1]), "=&v"(bf[2]), "=&v"(bf[3]), "=&v"(af[0]), "=&v"(af[1]), "=&v"(af[2]), "=&v"(af[3]),
;                 "=&v"(af[4]), "=&v"(af[5]), "=&v"(af[6]), "=&v"(af[7])
;               : "v"(la), "v"(lb)
;               : "memory");
;         } else {
;           asm volatile(
;               "ds_read_b128 %0, %9\n\tds_read_b128 %1, %9 offset:2048\n\tds_read_b128 %2, %9 offset:4096\n\tds_read_b128 %3, %9 offset:6144\n\t"
;               "ds_read_b128 %4, %8\n\tds_read_b128 %5, %8 offset:2048\n\tds_read_b128 %6, %8 offset:4096\n\tds_read_b128 %7, %8 offset:6144\n\t"
;               "s_waitcnt lgkmcnt(0)"
;               : "=&v"(bf[0]), "=&v"(bf[1]), "=&v"(bf[2]), "=&v"(bf[3]), "=&v"(af[0]), "=&v"(af[1]), "=&v"(af[2]), "=&v"(af[3])
;               : "v"(la), "v"(lb)
;               : "memory");
;         }
;       }
.Lg4_7_entry:
	s_mov_b32 s4, s29
	s_cmp_lt_u32 s28, 14
	s_cselect_b64 s[20:21], -1, 0
	s_lshl_b32 s4, s4, 16
	v_add3_u32 v242, s4, v104, v106
	v_add3_u32 v243, s4, v105, v106
	ds_read_b128 v[80:83], v243
	ds_read_b128 v[76:79], v243 offset:2048
	ds_read_b128 v[72:75], v243 offset:4096
	ds_read_b128 v[64:67], v243 offset:6144
	ds_read_b128 v[120:123], v242
	ds_read_b128 v[88:91], v242 offset:2048
	ds_read_b128 v[84:87], v242 offset:4096
	ds_read_b128 v[68:71], v242 offset:6144
	v_add3_u32 v242, s4, v104, v107
	v_add3_u32 v243, s4, v105, v107
	s_xor_b32 s29, s29, 1
	s_lshl_b32 s30, s29, 16
	v_readfirstlane_b32 s98, v102
	v_readfirstlane_b32 s99, v110
	v_readfirstlane_b32 s100, v103
	s_add_u32 s98, s98, s4
	s_add_u32 s99, s99, s4
	s_add_u32 s100, s100, s4
	s_sub_u32 vcc_lo, s30, s4
	s_add_u32 s98, s98, vcc_lo
	s_add_u32 s99, s99, vcc_lo
	s_add_u32 s100, s100, vcc_lo
	s_mov_b32 m0, s98
	s_nop 0
	global_load_lds_dwordx4 v[98:99], off
	s_add_u32 m0, s98, 0x400
	v_lshl_add_u64 v[254:255], v[98:99], 0, s[8:9]
	global_load_lds_dwordx4 v[254:255], off
	s_add_u32 m0, s99, 0x8000
	s_nop 0
	global_load_lds_dwordx4 v[96:97], off
	s_add_u32 m0, s100, 0x8400
	v_lshl_add_u64 v[254:255], v[96:97], 0, s[8:9]
	global_load_lds_dwordx4 v[254:255], off
	s_add_u32 m0, s100, 0x8800
	v_lshl_add_u64 v[254:255], v[96:97], 0, s[10:11]
	global_load_lds_dwordx4 v[254:255], off
	s_add_u32 m0, s100, 0x8c00
	v_lshl_add_u64 v[254:255], v[96:97], 0, s[12:13]
	global_load_lds_dwordx4 v[254:255], off
	s_sub_u32 s98, s98, vcc_lo
	s_sub_u32 s99, s99, vcc_lo
	s_sub_u32 s100, s100, vcc_lo
	s_mov_b64 s[4:5], 0x80
	v_lshl_add_u64 v[98:99], v[98:99], 0, s[4:5]
	v_lshl_add_u64 v[96:97], v[96:97], 0, s[4:5]
	s_branch .Lg4_7_mid

; #define GEMM_STAGE(BUF)                                                    \
;   do {                                                                     \
;     _Pragma("unroll") for (int i = 0; i < APW; ++i) GEMM_PIECE_A(BUF, i);  \
;     _Pragma("unroll") for (int i = 0; i < 4; ++i) GEMM_PIECE_B(BUF, i);    \
;     ag += 64; bg += 64;                                                    \
;   } while (0)
;     ...
;   if (preloaded) { ag += 64; bg += 64; }
;   else GEMM_STAGE(0);
;   GEMM_WAIT0;
;   int buf = 0;
; #pragma unroll 1
;   for (int kt = 0; kt < nk; ++kt) {
;     const bool issue = kt + 1 < nk;
;     const int ibuf = buf ^ 1;
; #pragma unroll
;     for (int s2 = 0; s2 < 2; ++s2) {
;       bf16x8 bf[4], af[MF];
;       {
;         const unsigned la = lds_base + buf * 65536 + ((wm * MF) << 11) + (s2 ? lofs1 : lofs0);
;         const unsigned lb = lds_base + buf * 65536 + 32768 + ((wn * 4) << 11) + (s2 ? lofs1 : lofs0);
;         if constexpr (MF == 8) {
;           asm volatile(
;               "ds_read_b128 %0, %13\n\tds_read_b128 %1, %13 offset:2048\n\tds_read_b128 %2, %13 offset:4096\n\tds_read_b128 %3, %13 offset:6144\n\t"
;               "ds_read_b128 %4, %12\n\tds_read_b128 %5, %12 offset:2048\n\tds_read_b128 %6, %12 offset:4096\n\tds_read_b128 %7, %12 offset:6144\n\t"
;               "ds_read_b128 %8, %12 offset:8192\n\tds_read_b128 %9, %12 offset:10240\n\tds_read_b128 %10, %12 offset:12288\n\tds_read_b128 %11, %12 offset:14336\n\t"
;               "s_waitcnt lgkmcnt(0)"
;               : "=&v"(bf[0]), "=&v"(bf[1]), "=&v"(bf[2]), "=&v"(bf[3]), "=&v"(af[0]), "=&v"(af[1]), "=&v"(af[2]), "=&v"(af[3]),
;                 "=&v"(af[4]), "=&v"(af[5]), "=&v"(af[6]), "=&v"(af[7])
;               : "v"(la), "v"(lb)
;               : "memory");
;         } else {
;           asm volatile(
;               "ds_read_b128 %0, %9\n\tds_read_b128 %1, %9 offset:2048\n\tds_read_b128 %2, %9 offset:4096\n\tds_read_b128 %3, %9 offset:6144\n\t"
;               "ds_read_b128 %4, %8\n\tds_read_b128 %5, %8 offset:2048\n\tds_read_b128 %6, %8 offset:4096\n\tds_read_b128 %7, %8 offset:6144\n\t"
;               "s_waitcnt lgkmcnt(0)"
;               : "=&v"(bf[0]), "=&v"(bf[1]), "=&v"(bf[2]), "=&v"(bf[3]), "=&v"(af[0]), "=&v"(af[1]), "=&v"(af[2]), "=&v"(af[3])
;               : "v"(la), "v"(lb)
;               : "memory");
;         }
;       }
.Lg4_8_entry:
	s_mov_b32 s2, s33
	s_cmp_gt_u32 s5, 2
	s_cselect_b64 s[0:1], -1, 0
	s_lshl_b32 s2, s2, 16
	v_add3_u32 v242, s2, v104, v106
	v_add3_u32 v243, s2, v105, v106
	ds_read_b128 v[80:83], v243
	ds_read_b128 v[76:79], v243 offset:2048
	ds_read_b128 v[72:75], v243 offset:4096
	ds_read_b128 v[64:67], v243 offset:6144
	ds_read_b128 v[120:123], v242
	ds_read_b128 v[88:91], v242 offset:2048
	ds_read_b128 v[84:87], v242 offset:4096
	ds_read_b128 v[68:71], v242 offset:6144
	v_add3_u32 v242, s2, v104, v107
	v_add3_u32 v243, s2, v105, v107
	s_xor_b32 s33, s33, 1
	s_lshl_b32 s34, s33, 16
	v_readfirstlane_b32 s98, v102
	v_readfirstlane_b32 s99, v111
	v_readfirstlane_b32 s100, v103
	s_add_u32 s98, s98, s2
	s_add_u32 s99, s99, s2
	s_add_u32 s100, s100, s2
	s_sub_u32 vcc_lo, s34, s2
	s_add_u32 s98, s98, vcc_lo
	s_add_u32 s99, s99, vcc_lo
	s_add_u32 s100, s100, vcc_lo
	s_mov_b32 m0, s98
	s_nop 0
	global_load_lds_dwordx4 v[96:97], off
	s_add_u32 m0, s98, 0x400
	v_lshl_add_u64 v[254:255], v[96:97], 0, s[6:7]
	global_load_lds_dwordx4 v[254:255], off
	s_add_u32 m0, s99, 0x8000
	s_nop 0
	global_load_lds_dwordx4 v[98:99], off
	s_add_u32 m0, s100, 0x8400
	v_lshl_add_u64 v[254:255], v[98:99], 0, s[6:7]
	global_load_lds_dwordx4 v[254:255], off
	s_add_u32 m0, s100, 0x8800
	v_lshl_add_u64 v[254:255], v[98:99], 0, s[8:9]
	global_load_lds_dwordx4 v[254:255], off
	s_add_u32 m0, s100, 0x8c00
	v_lshl_add_u64 v[254:255], v[98:99], 0, s[10:11]
	global_load_lds_dwordx4 v[254:255], off
	s_sub_u32 s98, s98, vcc_lo
	s_sub_u32 s99, s99, vcc_lo
	s_sub_u32 s100, s100, vcc_lo
	s_mov_b64 s[0:1], 0x80
	v_lshl_add_u64 v[96:97], v[96:97], 0, s[0:1]
	v_lshl_add_u64 v[98:99], v[98:99], 0, s[0:1]
	s_branch .Lg4_8_mid

;     ...
;   for (int kt = 0; kt < nk; ++kt) {
;     const bool issue = kt + 1 < nk;
;     const int ibuf = buf ^ 1;
; #pragma unroll
;     for (int s2 = 0; s2 < 2; ++s2) {
;       bf16x8 bf[4], af[MF];
;       {
;         const unsigned la = lds_base + buf * 65536 + ((wm * MF) << 11) + (s2 ? lofs1 : lofs0);
;         const unsigned lb = lds_base + buf * 65536 + 32768 + ((wn * 4) << 11) + (s2 ? lofs1 : lofs0);
;         if constexpr (MF == 8) {
;           asm volatile(
;               "ds_read_b128 %0, %13\n\tds_read_b128 %1, %13 offset:2048\n\tds_read_b128 %2, %13 offset:4096\n\tds_read_b128 %3, %13 offset:6144\n\t"
;               "ds_read_b128 %4, %12\n\tds_read_b128 %5, %12 offset:2048\n\tds_read_b128 %6, %12 offset:4096\n\tds_read_b128 %7, %12 offset:6144\n\t"
;               "ds_read_b128 %8, %12 offset:8192\n\tds_read_b128 %9, %12 offset:10240\n\tds_read_b128 %10, %12 offset:12288\n\tds_read_b128 %11, %12 offset:14336\n\t"
;               "s_waitcnt lgkmcnt(0)"
;               : "=&v"(bf[0]), "=&v"(bf[1]), "=&v"(bf[2]), "=&v"(bf[3]), "=&v"(af[0]), "=&v"(af[1]), "=&v"(af[2]), "=&v"(af[3]),
;                 "=&v"(af[4]), "=&v"(af[5]), "=&v"(af[6]), "=&v"(af[7])
;               : "v"(la), "v"(lb)
;               : "memory");
;         } else {
;           asm volatile(
;               "ds_read_b128 %0, %9\n\tds_read_b128 %1, %9 offset:2048\n\tds_read_b128 %2, %9 offset:4096\n\tds_read_b128 %3, %9 offset:6144\n\t"
;               "ds_read_b128 %4, %8\n\tds_read_b128 %5, %8 offset:2048\n\tds_read_b128 %6, %8 offset:4096\n\tds_read_b128 %7, %8 offset:6144\n\t"
;               "s_waitcnt lgkmcnt(0)"
;               : "=&v"(bf[0]), "=&v"(bf[1]), "=&v"(bf[2]), "=&v"(bf[3]), "=&v"(af[0]), "=&v"(af[1]), "=&v"(af[2]), "=&v"(af[3])
;               : "v"(la), "v"(lb)
;               : "memory");
;         }
;       }
;       __builtin_amdgcn_sched_barrier(0);
;       __builtin_amdgcn_s_setprio(1);
; #pragma unroll
;       for (int m = 0; m < MF; ++m) {
; #pragma unroll
;         for (int n = 0; n < 4; ++n) acc[m][n] = mfma16(bf[n], af[m], acc[m][n]);
;         if constexpr (MF == 8) {
;           if (m & 1) {
;             __builtin_amdgcn_sched_barrier(0);
;             if (issue) {
;               if (s2 == 0) { if (m == 1) GEMM_PIECE_A(ibuf, 0); if (m == 3) GEMM_PIECE_A(ibuf, 1); if (m == 5) GEMM_PIECE_A(ibuf, 2); if (m == 7) GEMM_PIECE_A(ibuf, 3); }
.LBB0_2005:
	s_mov_b32 s2, s29
	s_cmp_gt_u32 s5, 2
	s_cselect_b64 s[0:1], -1, 0
	s_lshl_b32 s2, s2, 16
	v_add3_u32 v242, s2, v104, v106
	v_add3_u32 v243, s2, v105, v106
	ds_read_b128 v[80:83], v243
	ds_read_b128 v[76:79], v243 offset:2048
	ds_read_b128 v[72:75], v243 offset:4096
	ds_read_b128 v[64:67], v243 offset:6144
	ds_read_b128 v[120:123], v242
	ds_read_b128 v[88:91], v242 offset:2048
	ds_read_b128 v[84:87], v242 offset:4096
	ds_read_b128 v[68:71], v242 offset:6144
	v_add3_u32 v242, s2, v104, v107
	v_add3_u32 v243, s2, v105, v107
	s_xor_b32 s29, s29, 1
	s_lshl_b32 s30, s29, 16
	v_readfirstlane_b32 s98, v102
	v_readfirstlane_b32 s99, v111
	v_readfirstlane_b32 s100, v103
	s_add_u32 s98, s98, s2
	s_add_u32 s99, s99, s2
	s_add_u32 s100, s100, s2
	s_setprio 1
	v_mfma_f32_16x16x32_bf16 v[60:63], v[208:211], v[224:227], v[60:63]
	v_mfma_f32_16x16x32_bf16 v[56:59], v[212:215], v[224:227], v[56:59]
	v_mfma_f32_16x16x32_bf16 v[52:55], v[216:219], v[224:227], v[52:55]
	v_mfma_f32_16x16x32_bf16 v[48:51], v[220:223], v[224:227], v[48:51]
	v_mfma_f32_16x16x32_bf16 v[44:47], v[208:211], v[228:231], v[44:47]
	v_mfma_f32_16x16x32_bf16 v[40:43], v[212:215], v[228:231], v[40:43]
	v_mfma_f32_16x16x32_bf16 v[36:39], v[216:219], v[228:231], v[36:39]
	v_mfma_f32_16x16x32_bf16 v[32:35], v[220:223], v[228:231], v[32:35]
	v_mfma_f32_16x16x32_bf16 v[28:31], v[208:211], v[232:235], v[28:31]
	v_mfma_f32_16x16x32_bf16 v[24:27], v[212:215], v[232:235], v[24:27]
	v_mfma_f32_16x16x32_bf16 v[20:23], v[216:219], v[232:235], v[20:23]
	v_mfma_f32_16x16x32_bf16 v[12:15], v[220:223], v[232:235], v[12:15]
	v_mfma_f32_16x16x32_bf16 v[16:19], v[208:211], v[238:241], v[16:19]
	v_mfma_f32_16x16x32_bf16 v[8:11], v[212:215], v[238:241], v[8:11]
	v_mfma_f32_16x16x32_bf16 v[4:7], v[216:219], v[238:241], v[4:7]
	v_mfma_f32_16x16x32_bf16 v[0:3], v[220:223], v[238:241], v[0:3]
	s_setprio 0

; #define GEMM_STAGE(BUF)                                                    \
;   do {                                                                     \
;     _Pragma("unroll") for (int i = 0; i < APW; ++i) GEMM_PIECE_A(BUF, i);  \
;     _Pragma("unroll") for (int i = 0; i < 4; ++i) GEMM_PIECE_B(BUF, i);    \
;     ag += 64; bg += 64;                                                    \
;   } while (0)
;     ...
;   if (preloaded) { ag += 64; bg += 64; }
;   else GEMM_STAGE(0);
;   GEMM_WAIT0;
;   int buf = 0;
; #pragma unroll 1
;   for (int kt = 0; kt < nk; ++kt) {
;     const bool issue = kt + 1 < nk;
;     const int ibuf = buf ^ 1;
; #pragma unroll
;     for (int s2 = 0; s2 < 2; ++s2) {
;       bf16x8 bf[4], af[MF];
;       {
;         const unsigned la = lds_base + buf * 65536 + ((wm * MF) << 11) + (s2 ? lofs1 : lofs0);
;         const unsigned lb = lds_base + buf * 65536 + 32768 + ((wn * 4) << 11) + (s2 ? lofs1 : lofs0);
;         if constexpr (MF == 8) {
;           asm volatile(
;               "ds_read_b128 %0, %13\n\tds_read_b128 %1, %13 offset:2048\n\tds_read_b128 %2, %13 offset:4096\n\tds_read_b128 %3, %13 offset:6144\n\t"
;               "ds_read_b128 %4, %12\n\tds_read_b128 %5, %12 offset:2048\n\tds_read_b128 %6, %12 offset:4096\n\tds_read_b128 %7, %12 offset:6144\n\t"
;               "ds_read_b128 %8, %12 offset:8192\n\tds_read_b128 %9, %12 offset:10240\n\tds_read_b128 %10, %12 offset:12288\n\tds_read_b128 %11, %12 offset:14336\n\t"
;               "s_waitcnt lgkmcnt(0)"
;               : "=&v"(bf[0]), "=&v"(bf[1]), "=&v"(bf[2]), "=&v"(bf[3]), "=&v"(af[0]), "=&v"(af[1]), "=&v"(af[2]), "=&v"(af[3]),
;                 "=&v"(af[4]), "=&v"(af[5]), "=&v"(af[6]), "=&v"(af[7])
;               : "v"(la), "v"(lb)
;               : "memory");
;         } else {
;           asm volatile(
;               "ds_read_b128 %0, %9\n\tds_read_b128 %1, %9 offset:2048\n\tds_read_b128 %2, %9 offset:4096\n\tds_read_b128 %3, %9 offset:6144\n\t"
;               "ds_read_b128 %4, %8\n\tds_read_b128 %5, %8 offset:2048\n\tds_read_b128 %6, %8 offset:4096\n\tds_read_b128 %7, %8 offset:6144\n\t"
;               "s_waitcnt lgkmcnt(0)"
;               : "=&v"(bf[0]), "=&v"(bf[1]), "=&v"(bf[2]), "=&v"(bf[3]), "=&v"(af[0]), "=&v"(af[1]), "=&v"(af[2]), "=&v"(af[3])
;               : "v"(la), "v"(lb)
;               : "memory");
;         }
;       }
.Lg4_9_entry:
	s_mov_b32 s2, s29
	s_cmp_gt_u32 s5, 2
	s_cselect_b64 s[0:1], -1, 0
	s_lshl_b32 s2, s2, 16
	v_add3_u32 v242, s2, v104, v106
	v_add3_u32 v243, s2, v105, v106
	ds_read_b128 v[80:83], v243
	ds_read_b128 v[76:79], v243 offset:2048
	ds_read_b128 v[72:75], v243 offset:4096
	ds_read_b128 v[64:67], v243 offset:6144
	ds_read_b128 v[120:123], v242
	ds_read_b128 v[88:91], v242 offset:2048
	ds_read_b128 v[84:87], v242 offset:4096
	ds_read_b128 v[68:71], v242 offset:6144
	v_add3_u32 v242, s2, v104, v107
	v_add3_u32 v243, s2, v105, v107
	s_xor_b32 s29, s29, 1
	s_lshl_b32 s30, s29, 16
	v_readfirstlane_b32 s98, v102
	v_readfirstlane_b32 s99, v111
	v_readfirstlane_b32 s100, v103
	s_add_u32 s98, s98, s2
	s_add_u32 s99, s99, s2
	s_add_u32 s100, s100, s2
	s_sub_u32 vcc_lo, s30, s2
	s_add_u32 s98, s98, vcc_lo
	s_add_u32 s99, s99, vcc_lo
	s_add_u32 s100, s100, vcc_lo
	s_mov_b32 m0, s98
	s_nop 0
	global_load_lds_dwordx4 v[96:97], off
	s_add_u32 m0, s98, 0x400
	v_lshl_add_u64 v[254:255], v[96:97], 0, s[6:7]
	global_load_lds_dwordx4 v[254:255], off
	s_add_u32 m0, s99, 0x8000
	s_nop 0
	global_load_lds_dwordx4 v[98:99], off
	s_add_u32 m0, s100, 0x8400
	v_lshl_add_u64 v[254:255], v[98:99], 0, s[6:7]
	global_load_lds_dwordx4 v[254:255], off
	s_add_u32 m0, s100, 0x8800
	v_lshl_add_u64 v[254:255], v[98:99], 0, s[8:9]
	global_load_lds_dwordx4 v[254:255], off
	s_add_u32 m0, s100, 0x8c00
	v_lshl_add_u64 v[254:255], v[98:99], 0, s[10:11]
	global_load_lds_dwordx4 v[254:255], off
	s_sub_u32 s98, s98, vcc_lo
	s_sub_u32 s99, s99, vcc_lo
	s_sub_u32 s100, s100, vcc_lo
	s_mov_b64 s[0:1], 0x80
	v_lshl_add_u64 v[96:97], v[96:97], 0, s[0:1]
	v_lshl_add_u64 v[98:99], v[98:99], 0, s[0:1]
	s_branch .Lg4_9_mid

;     ...
;   for (int kt = 0; kt < nk; ++kt) {
;     const bool issue = kt + 1 < nk;
;     const int ibuf = buf ^ 1;
; #pragma unroll
;     for (int s2 = 0; s2 < 2; ++s2) {
;       bf16x8 bf[4], af[MF];
;       {
;         const unsigned la = lds_base + buf * 65536 + ((wm * MF) << 11) + (s2 ? lofs1 : lofs0);
;         const unsigned lb = lds_base + buf * 65536 + 32768 + ((wn * 4) << 11) + (s2 ? lofs1 : lofs0);
;         if constexpr (MF == 8) {
;           asm volatile(
;               "ds_read_b128 %0, %13\n\tds_read_b128 %1, %13 offset:2048\n\tds_read_b128 %2, %13 offset:4096\n\tds_read_b128 %3, %13 offset:6144\n\t"
;               "ds_read_b128 %4, %12\n\tds_read_b128 %5, %12 offset:2048\n\tds_read_b128 %6, %12 offset:4096\n\tds_read_b128 %7, %12 offset:6144\n\t"
;               "ds_read_b128 %8, %12 offset:8192\n\tds_read_b128 %9, %12 offset:10240\n\tds_read_b128 %10, %12 offset:12288\n\tds_read_b128 %11, %12 offset:14336\n\t"
;               "s_waitcnt lgkmcnt(0)"
;               : "=&v"(bf[0]), "=&v"(bf[1]), "=&v"(bf[2]), "=&v"(bf[3]), "=&v"(af[0]), "=&v"(af[1]), "=&v"(af[2]), "=&v"(af[3]),
;                 "=&v"(af[4]), "=&v"(af[5]), "=&v"(af[6]), "=&v"(af[7])
;               : "v"(la), "v"(lb)
;               : "memory");
;         } else {
;           asm volatile(
;               "ds_read_b128 %0, %9\n\tds_read_b128 %1, %9 offset:2048\n\tds_read_b128 %2, %9 offset:4096\n\tds_read_b128 %3, %9 offset:6144\n\t"
;               "ds_read_b128 %4, %8\n\tds_read_b128 %5, %8 offset:2048\n\tds_read_b128 %6, %8 offset:4096\n\tds_read_b128 %7, %8 offset:6144\n\t"
;               "s_waitcnt lgkmcnt(0)"
;               : "=&v"(bf[0]), "=&v"(bf[1]), "=&v"(bf[2]), "=&v"(bf[3]), "=&v"(af[0]), "=&v"(af[1]), "=&v"(af[2]), "=&v"(af[3])
;               : "v"(la), "v"(lb)
;               : "memory");
;         }
;       }
;       __builtin_amdgcn_sched_barrier(0);
;       __builtin_amdgcn_s_setprio(1);
; #pragma unroll
;       for (int m = 0; m < MF; ++m) {
; #pragma unroll
;         for (int n = 0; n < 4; ++n) acc[m][n] = mfma16(bf[n], af[m], acc[m][n]);
;         if constexpr (MF == 8) {
;           if (m & 1) {
;             __builtin_amdgcn_sched_barrier(0);
;             if (issue) {
;               if (s2 == 0) { if (m == 1) GEMM_PIECE_A(ibuf, 0); if (m == 3) GEMM_PIECE_A(ibuf, 1); if (m == 5) GEMM_PIECE_A(ibuf, 2); if (m == 7) GEMM_PIECE_A(ibuf, 3); }
.LBB0_2176:
	s_mov_b32 s4, s35
	s_cmp_lt_u32 s34, 42
	s_cselect_b64 s[24:25], -1, 0
	s_lshl_b32 s4, s4, 16
	v_add3_u32 v242, s4, v104, v106
	v_add3_u32 v243, s4, v105, v106
	ds_read_b128 v[80:83], v243
	ds_read_b128 v[76:79], v243 offset:2048
	ds_read_b128 v[72:75], v243 offset:4096
	ds_read_b128 v[64:67], v243 offset:6144
	ds_read_b128 v[120:123], v242
	ds_read_b128 v[88:91], v242 offset:2048
	ds_read_b128 v[84:87], v242 offset:4096
	ds_read_b128 v[68:71], v242 offset:6144
	v_add3_u32 v242, s4, v104, v107
	v_add3_u32 v243, s4, v105, v107
	s_xor_b32 s35, s35, 1
	s_lshl_b32 s36, s35, 16
	v_readfirstlane_b32 s98, v102
	v_readfirstlane_b32 s99, v110
	v_readfirstlane_b32 s100, v103
	s_add_u32 s98, s98, s4
	s_add_u32 s99, s99, s4
	s_add_u32 s100, s100, s4
	s_setprio 1
	v_mfma_f32_16x16x32_bf16 v[60:63], v[208:211], v[224:227], v[60:63]
	v_mfma_f32_16x16x32_bf16 v[56:59], v[212:215], v[224:227], v[56:59]
	v_mfma_f32_16x16x32_bf16 v[52:55], v[216:219], v[224:227], v[52:55]
	v_mfma_f32_16x16x32_bf16 v[48:51], v[220:223], v[224:227], v[48:51]
	v_mfma_f32_16x16x32_bf16 v[44:47], v[208:211], v[228:231], v[44:47]
	v_mfma_f32_16x16x32_bf16 v[40:43], v[212:215], v[228:231], v[40:43]
	v_mfma_f32_16x16x32_bf16 v[28:31], v[216:219], v[228:231], v[28:31]
	v_mfma_f32_16x16x32_bf16 v[20:23], v[220:223], v[228:231], v[20:23]
	v_mfma_f32_16x16x32_bf16 v[36:39], v[208:211], v[232:235], v[36:39]
	v_mfma_f32_16x16x32_bf16 v[32:35], v[212:215], v[232:235], v[32:35]
	v_mfma_f32_16x16x32_bf16 v[24:27], v[216:219], v[232:235], v[24:27]
	v_mfma_f32_16x16x32_bf16 v[16:19], v[220:223], v[232:235], v[16:19]
	v_mfma_f32_16x16x32_bf16 v[12:15], v[208:211], v[238:241], v[12:15]
	v_mfma_f32_16x16x32_bf16 v[8:11], v[212:215], v[238:241], v[8:11]
	v_mfma_f32_16x16x32_bf16 v[4:7], v[216:219], v[238:241], v[4:7]
	v_mfma_f32_16x16x32_bf16 v[0:3], v[220:223], v[238:241], v[0:3]
	s_setprio 0

; #define GEMM_STAGE(BUF)                                                    \
;   do {                                                                     \
;     _Pragma("unroll") for (int i = 0; i < APW; ++i) GEMM_PIECE_A(BUF, i);  \
;     _Pragma("unroll") for (int i = 0; i < 4; ++i) GEMM_PIECE_B(BUF, i);    \
;     ag += 64; bg += 64;                                                    \
;   } while (0)
;     ...
;   if (preloaded) { ag += 64; bg += 64; }
;   else GEMM_STAGE(0);
;   GEMM_WAIT0;
;   int buf = 0;
; #pragma unroll 1
;   for (int kt = 0; kt < nk; ++kt) {
;     const bool issue = kt + 1 < nk;
;     const int ibuf = buf ^ 1;
; #pragma unroll
;     for (int s2 = 0; s2 < 2; ++s2) {
;       bf16x8 bf[4], af[MF];
;       {
;         const unsigned la = lds_base + buf * 65536 + ((wm * MF) << 11) + (s2 ? lofs1 : lofs0);
;         const unsigned lb = lds_base + buf * 65536 + 32768 + ((wn * 4) << 11) + (s2 ? lofs1 : lofs0);
;         if constexpr (MF == 8) {
;           asm volatile(
;               "ds_read_b128 %0, %13\n\tds_read_b128 %1, %13 offset:2048\n\tds_read_b128 %2, %13 offset:4096\n\tds_read_b128 %3, %13 offset:6144\n\t"
;               "ds_read_b128 %4, %12\n\tds_read_b128 %5, %12 offset:2048\n\tds_read_b128 %6, %12 offset:4096\n\tds_read_b128 %7, %12 offset:6144\n\t"
;               "ds_read_b128 %8, %12 offset:8192\n\tds_read_b128 %9, %12 offset:10240\n\tds_read_b128 %10, %12 offset:12288\n\tds_read_b128 %11, %12 offset:14336\n\t"
;               "s_waitcnt lgkmcnt(0)"
;               : "=&v"(bf[0]), "=&v"(bf[1]), "=&v"(bf[2]), "=&v"(bf[3]), "=&v"(af[0]), "=&v"(af[1]), "=&v"(af[2]), "=&v"(af[3]),
;                 "=&v"(af[4]), "=&v"(af[5]), "=&v"(af[6]), "=&v"(af[7])
;               : "v"(la), "v"(lb)
;               : "memory");
;         } else {
;           asm volatile(
;               "ds_read_b128 %0, %9\n\tds_read_b128 %1, %9 offset:2048\n\tds_read_b128 %2, %9 offset:4096\n\tds_read_b128 %3, %9 offset:6144\n\t"
;               "ds_read_b128 %4, %8\n\tds_read_b128 %5, %8 offset:2048\n\tds_read_b128 %6, %8 offset:4096\n\tds_read_b128 %7, %8 offset:6144\n\t"
;               "s_waitcnt lgkmcnt(0)"
;               : "=&v"(bf[0]), "=&v"(bf[1]), "=&v"(bf[2]), "=&v"(bf[3]), "=&v"(af[0]), "=&v"(af[1]), "=&v"(af[2]), "=&v"(af[3])
;               : "v"(la), "v"(lb)
;               : "memory");
;         }
;       }
.Lg4_10_entry:
	s_mov_b32 s4, s35
	s_cmp_lt_u32 s34, 42
	s_cselect_b64 s[24:25], -1, 0
	s_lshl_b32 s4, s4, 16
	v_add3_u32 v242, s4, v104, v106
	v_add3_u32 v243, s4, v105, v106
	ds_read_b128 v[80:83], v243
	ds_read_b128 v[76:79], v243 offset:2048
	ds_read_b128 v[72:75], v243 offset:4096
	ds_read_b128 v[64:67], v243 offset:6144
	ds_read_b128 v[120:123], v242
	ds_read_b128 v[88:91], v242 offset:2048
	ds_read_b128 v[84:87], v242 offset:4096
	ds_read_b128 v[68:71], v242 offset:6144
	v_add3_u32 v242, s4, v104, v107
	v_add3_u32 v243, s4, v105, v107
	s_xor_b32 s35, s35, 1
	s_lshl_b32 s36, s35, 16
	v_readfirstlane_b32 s98, v102
	v_readfirstlane_b32 s99, v110
	v_readfirstlane_b32 s100, v103
	s_add_u32 s98, s98, s4
	s_add_u32 s99, s99, s4
	s_add_u32 s100, s100, s4
	s_sub_u32 vcc_lo, s36, s4
	s_add_u32 s98, s98, vcc_lo
	s_add_u32 s99, s99, vcc_lo
	s_add_u32 s100, s100, vcc_lo
	s_mov_b32 m0, s98
	s_nop 0
	global_load_lds_dwordx4 v[98:99], off
	s_add_u32 m0, s98, 0x400
	v_lshl_add_u64 v[254:255], v[98:99], 0, s[12:13]
	global_load_lds_dwordx4 v[254:255], off
	s_add_u32 m0, s99, 0x8000
	s_nop 0
	global_load_lds_dwordx4 v[96:97], off
	s_add_u32 m0, s100, 0x8400
	v_lshl_add_u64 v[254:255], v[96:97], 0, s[12:13]
	global_load_lds_dwordx4 v[254:255], off
	s_add_u32 m0, s100, 0x8800
	v_lshl_add_u64 v[254:255], v[96:97], 0, s[14:15]
	global_load_lds_dwordx4 v[254:255], off
	s_add_u32 m0, s100, 0x8c00
	v_lshl_add_u64 v[254:255], v[96:97], 0, s[16:17]
	global_load_lds_dwordx4 v[254:255], off
	s_sub_u32 s98, s98, vcc_lo
	s_sub_u32 s99, s99, vcc_lo
	s_sub_u32 s100, s100, vcc_lo
	s_mov_b64 s[4:5], 0x80
	v_lshl_add_u64 v[98:99], v[98:99], 0, s[4:5]
	v_lshl_add_u64 v[96:97], v[96:97], 0, s[4:5]
	s_branch .Lg4_10_mid
